# GEMM K loops: the priority drop/raise pair between the two 16-MFMA groups of a block removed (one raise per block)
# speedup vs baseline: 1.0056x; 1.0017x over previous
; #define PG8_STAGE(bufoff, gbase, voff) do { _Pragma("unroll") for (int _i = 0; _i < 2; ++_i) \
;         __builtin_amdgcn_global_load_lds((const unsigned*)((const char*)(gbase) + (voff)[_i]), (PG8_LAS unsigned*)(lds + (bufoff) + ldsw + _i * 8192), 16, 0, 0); } while (0)
; #define PG8_LDA(dst, b, h) do { _Pragma("unroll") for (int m = 0; m < 4; ++m) _Pragma("unroll") for (int k = 0; k < 2; ++k) dst[m][k] = *(const PG8_LAS bf16x8*)(lds + PG8_SA(b, h) + aoff + m * 2048 + k * 1024); } while (0)
; #define PG8_LDB(dst, b, h) do { _Pragma("unroll") for (int n = 0; n < 2; ++n) _Pragma("unroll") for (int k = 0; k < 2; ++k) dst[n][k] = *(const PG8_LAS bf16x8*)(lds + PG8_SB(b, h) + boff + n * 2048 + k * 1024); } while (0)
; #define PG8_MMA(ai, bj, At, Bt) do { __builtin_amdgcn_s_setprio(1); _Pragma("unroll") for (int m = 0; m < 4; ++m) _Pragma("unroll") for (int n = 0; n < 2; ++n) _Pragma("unroll") for (int k = 0; k < 2; ++k) \
;         acc[ai][bj][m][n] = __builtin_amdgcn_mfma_f32_16x16x32_bf16(Bt[n][k], At[m][k], acc[ai][bj][m][n], 0, 0, 0); __builtin_amdgcn_s_setprio(0); } while (0)
; #define PG8_WAIT_V(n) asm volatile("s_waitcnt vmcnt(" #n ")" ::: "memory")
; #define PG8_WAIT_L(n) asm volatile("s_waitcnt lgkmcnt(" #n ")" ::: "memory")
; #define PG8_BAR __builtin_amdgcn_s_barrier()
; #define PG8_SCHED __builtin_amdgcn_sched_barrier(0)
; template <class Epi, class Sched, bool ALIGN_EPI = false, bool SP2 = false>
; __device__ __forceinline__ void gemm_phase(PG8_LAS unsigned char* lds, const Gemm g, const Sched& S, const Epi& E) {
;     ...
;             PG8_LDB(B0, 0, 0); PG8_LDB(B1, 0, 1); PG8_SCHED; PG8_LDA(At, 0, 0); PG8_STAGE(PG8_SA(1, 1), a1 + hstep, voffA);
;             PG8_WAIT_V(8); PG8_WAIT_L(0); PG8_BAR; PG8_MMA(0, 0, At, B0); PG8_MMA(0, 1, At, B1); PG8_BAR; PG8_SCHED;
;             PG8_LDA(At, 0, 1); PG8_STAGE(PG8_SB(0, 0), b2, voffB); PG8_STAGE(PG8_SB(0, 1), b2 + hstep, voffB); PG8_STAGE(PG8_SA(0, 0), a2, voffA);
.LBB0_38:
	s_add_u32 s10, vcc_lo, 0xfff80080
	s_addc_u32 s11, vcc_hi, -1
	s_add_i32 s84, 0, 0x10000
	s_cmp_eq_u32 s13, 28
	s_cselect_b32 s69, s27, s11
	s_cselect_b32 s68, s86, s10
	s_cselect_b32 s11, s17, s12
	s_cselect_b32 s10, s88, s21
	s_add_i32 s93, 0, 0x14000
	v_add_u32_e32 v138, s84, v194
	v_add_u32_e32 v164, s93, v194
	ds_read_b128 v[114:117], v138
	ds_read_b128 v[118:121], v138 offset:1024
	ds_read_b128 v[130:133], v138 offset:2048
	ds_read_b128 v[138:141], v138 offset:3072
	ds_read_b128 v[146:149], v164
	ds_read_b128 v[156:159], v164 offset:1024
	ds_read_b128 v[160:163], v164 offset:2048
	ds_read_b128 v[164:167], v164 offset:3072
	v_lshl_add_u64 v[208:209], vcc, 0, v[152:153]
	s_add_i32 m0, s2, 0xc000
	ds_read_b128 v[168:171], v199
	ds_read_b128 v[172:175], v199 offset:1024
	ds_read_b128 v[176:179], v199 offset:2048
	ds_read_b128 v[180:183], v199 offset:3072
	ds_read_b128 v[184:187], v199 offset:4096
	ds_read_b128 v[188:191], v199 offset:5120
	ds_read_b128 v[200:203], v199 offset:6144
	ds_read_b128 v[204:207], v199 offset:7168
	global_load_lds_dwordx4 v[208:209], off
	v_lshl_add_u64 v[208:209], vcc, 0, v[154:155]
	s_add_i32 m0, s2, 0xe000
	s_nop 0
	global_load_lds_dwordx4 v[208:209], off
	s_waitcnt vmcnt(8)
	s_waitcnt lgkmcnt(0)
	s_setprio 1
	s_barrier
	v_mfma_f32_16x16x32_bf16 v[142:145], v[114:117], v[168:171], v[142:145]
	v_mfma_f32_16x16x32_bf16 v[62:65], v[130:133], v[168:171], v[62:65]
	v_mfma_f32_16x16x32_bf16 v[122:125], v[114:117], v[176:179], v[122:125]
	v_mfma_f32_16x16x32_bf16 v[50:53], v[130:133], v[176:179], v[50:53]
	v_mfma_f32_16x16x32_bf16 v[106:109], v[114:117], v[184:187], v[106:109]
	v_mfma_f32_16x16x32_bf16 v[42:45], v[130:133], v[184:187], v[42:45]
	v_mfma_f32_16x16x32_bf16 v[98:101], v[114:117], v[200:203], v[98:101]
	v_mfma_f32_16x16x32_bf16 v[34:37], v[130:133], v[200:203], v[34:37]
	v_mfma_f32_16x16x32_bf16 v[142:145], v[118:121], v[172:175], v[142:145]
	v_mfma_f32_16x16x32_bf16 v[62:65], v[138:141], v[172:175], v[62:65]
	v_mfma_f32_16x16x32_bf16 v[122:125], v[118:121], v[180:183], v[122:125]
	v_mfma_f32_16x16x32_bf16 v[50:53], v[138:141], v[180:183], v[50:53]
	v_mfma_f32_16x16x32_bf16 v[106:109], v[118:121], v[188:191], v[106:109]
	v_mfma_f32_16x16x32_bf16 v[42:45], v[138:141], v[188:191], v[42:45]
	v_mfma_f32_16x16x32_bf16 v[98:101], v[118:121], v[204:207], v[98:101]
	v_mfma_f32_16x16x32_bf16 v[34:37], v[138:141], v[204:207], v[34:37]
	v_mfma_f32_16x16x32_bf16 v[134:137], v[146:149], v[168:171], v[134:137]
	v_mfma_f32_16x16x32_bf16 v[58:61], v[160:163], v[168:171], v[58:61]
	v_mfma_f32_16x16x32_bf16 v[126:129], v[146:149], v[176:179], v[126:129]
	v_mfma_f32_16x16x32_bf16 v[54:57], v[160:163], v[176:179], v[54:57]
	v_mfma_f32_16x16x32_bf16 v[110:113], v[146:149], v[184:187], v[110:113]
	v_mfma_f32_16x16x32_bf16 v[46:49], v[160:163], v[184:187], v[46:49]
	v_mfma_f32_16x16x32_bf16 v[102:105], v[146:149], v[200:203], v[102:105]
	v_mfma_f32_16x16x32_bf16 v[38:41], v[160:163], v[200:203], v[38:41]
	v_mfma_f32_16x16x32_bf16 v[134:137], v[156:159], v[172:175], v[134:137]
	v_mfma_f32_16x16x32_bf16 v[58:61], v[164:167], v[172:175], v[58:61]
	v_mfma_f32_16x16x32_bf16 v[126:129], v[156:159], v[180:183], v[126:129]
	v_mfma_f32_16x16x32_bf16 v[54:57], v[164:167], v[180:183], v[54:57]
	v_mfma_f32_16x16x32_bf16 v[110:113], v[156:159], v[188:191], v[110:113]
	v_mfma_f32_16x16x32_bf16 v[46:49], v[164:167], v[188:191], v[46:49]
	v_mfma_f32_16x16x32_bf16 v[102:105], v[156:159], v[204:207], v[102:105]
	v_mfma_f32_16x16x32_bf16 v[38:41], v[164:167], v[204:207], v[38:41]
	s_barrier
	s_setprio 0
	s_add_i32 s84, s84, s1
	v_lshl_add_u64 v[208:209], s[10:11], 0, v[0:1]
	s_mov_b32 m0, s84
	ds_read_b128 v[168:171], v199 offset:16384
	ds_read_b128 v[172:175], v199 offset:17408
	ds_read_b128 v[176:179], v199 offset:18432
	ds_read_b128 v[180:183], v199 offset:19456
	ds_read_b128 v[184:187], v199 offset:20480
	ds_read_b128 v[188:191], v199 offset:21504
	ds_read_b128 v[200:203], v199 offset:22528
	ds_read_b128 v[204:207], v199 offset:23552
	global_load_lds_dwordx4 v[208:209], off
	s_add_i32 m0, s84, 0x2000
	s_add_u32 s84, s10, 0x80000
	v_lshl_add_u64 v[210:211], s[10:11], 0, v[150:151]
	s_addc_u32 s85, s11, 0
	s_add_i32 s93, s93, s1
	global_load_lds_dwordx4 v[210:211], off
	v_lshl_add_u64 v[212:213], s[84:85], 0, v[0:1]
	s_mov_b32 m0, s93
	v_lshl_add_u64 v[214:215], s[68:69], 0, v[150:151]
	global_load_lds_dwordx4 v[212:213], off
	v_lshl_add_u64 v[212:213], s[84:85], 0, v[150:151]
	s_add_i32 m0, s93, 0x2000
	s_nop 0
	global_load_lds_dwordx4 v[212:213], off
	v_lshl_add_u64 v[212:213], s[68:69], 0, v[0:1]
	s_mov_b32 m0, s2
	s_nop 0
	global_load_lds_dwordx4 v[212:213], off
	s_mov_b32 m0, s4
	s_nop 0
	global_load_lds_dwordx4 v[214:215], off
	s_waitcnt vmcnt(8)
	s_waitcnt lgkmcnt(0)
	s_setprio 1
	s_barrier
; #define PG8_STAGE(bufoff, gbase, voff) do { _Pragma("unroll") for (int _i = 0; _i < 2; ++_i) \
;         __builtin_amdgcn_global_load_lds((const unsigned*)((const char*)(gbase) + (voff)[_i]), (PG8_LAS unsigned*)(lds + (bufoff) + ldsw + _i * 8192), 16, 0, 0); } while (0)
; #define PG8_LDA(dst, b, h) do { _Pragma("unroll") for (int m = 0; m < 4; ++m) _Pragma("unroll") for (int k = 0; k < 2; ++k) dst[m][k] = *(const PG8_LAS bf16x8*)(lds + PG8_SA(b, h) + aoff + m * 2048 + k * 1024); } while (0)
; #define PG8_LDB(dst, b, h) do { _Pragma("unroll") for (int n = 0; n < 2; ++n) _Pragma("unroll") for (int k = 0; k < 2; ++k) dst[n][k] = *(const PG8_LAS bf16x8*)(lds + PG8_SB(b, h) + boff + n * 2048 + k * 1024); } while (0)
; #define PG8_MMA(ai, bj, At, Bt) do { __builtin_amdgcn_s_setprio(1); _Pragma("unroll") for (int m = 0; m < 4; ++m) _Pragma("unroll") for (int n = 0; n < 2; ++n) _Pragma("unroll") for (int k = 0; k < 2; ++k) \
;         acc[ai][bj][m][n] = __builtin_amdgcn_mfma_f32_16x16x32_bf16(Bt[n][k], At[m][k], acc[ai][bj][m][n], 0, 0, 0); __builtin_amdgcn_s_setprio(0); } while (0)
; #define PG8_WAIT_V(n) asm volatile("s_waitcnt vmcnt(" #n ")" ::: "memory")
; #define PG8_WAIT_L(n) asm volatile("s_waitcnt lgkmcnt(" #n ")" ::: "memory")
; #define PG8_BAR __builtin_amdgcn_s_barrier()
; #define PG8_SCHED __builtin_amdgcn_sched_barrier(0)
; template <class Epi, class Sched, bool ALIGN_EPI = false, bool SP2 = false>
; __device__ __forceinline__ void gemm_phase(PG8_LAS unsigned char* lds, const Gemm g, const Sched& S, const Epi& E) {
;     ...
;             PG8_WAIT_V(8); PG8_WAIT_L(0); PG8_BAR; PG8_MMA(1, 0, At, B0); PG8_MMA(1, 1, At, B1); PG8_BAR; PG8_SCHED;
;             PG8_LDB(B0, 1, 0); PG8_LDB(B1, 1, 1); PG8_SCHED; PG8_LDA(At, 1, 0); PG8_STAGE(PG8_SA(0, 1), a2 + hstep, voffA);
;             PG8_WAIT_V(8); PG8_WAIT_L(0); PG8_BAR; PG8_MMA(0, 0, At, B0); PG8_MMA(0, 1, At, B1); PG8_BAR; PG8_SCHED;
	v_mfma_f32_16x16x32_bf16 v[94:97], v[114:117], v[168:171], v[94:97]
	v_mfma_f32_16x16x32_bf16 v[30:33], v[130:133], v[168:171], v[30:33]
	v_mfma_f32_16x16x32_bf16 v[82:85], v[114:117], v[176:179], v[82:85]
	v_mfma_f32_16x16x32_bf16 v[18:21], v[130:133], v[176:179], v[18:21]
	v_mfma_f32_16x16x32_bf16 v[74:77], v[114:117], v[184:187], v[74:77]
	v_mfma_f32_16x16x32_bf16 v[10:13], v[130:133], v[184:187], v[10:13]
	v_mfma_f32_16x16x32_bf16 v[66:69], v[114:117], v[200:203], v[66:69]
	v_mfma_f32_16x16x32_bf16 v[2:5], v[130:133], v[200:203], v[2:5]
	v_mfma_f32_16x16x32_bf16 v[94:97], v[118:121], v[172:175], v[94:97]
	v_mfma_f32_16x16x32_bf16 v[30:33], v[138:141], v[172:175], v[30:33]
	v_mfma_f32_16x16x32_bf16 v[82:85], v[118:121], v[180:183], v[82:85]
	v_mfma_f32_16x16x32_bf16 v[18:21], v[138:141], v[180:183], v[18:21]
	v_mfma_f32_16x16x32_bf16 v[74:77], v[118:121], v[188:191], v[74:77]
	v_mfma_f32_16x16x32_bf16 v[10:13], v[138:141], v[188:191], v[10:13]
	v_mfma_f32_16x16x32_bf16 v[66:69], v[118:121], v[204:207], v[66:69]
	v_mfma_f32_16x16x32_bf16 v[2:5], v[138:141], v[204:207], v[2:5]
	v_mfma_f32_16x16x32_bf16 v[90:93], v[146:149], v[168:171], v[90:93]
	v_mfma_f32_16x16x32_bf16 v[26:29], v[160:163], v[168:171], v[26:29]
	v_mfma_f32_16x16x32_bf16 v[86:89], v[146:149], v[176:179], v[86:89]
	v_mfma_f32_16x16x32_bf16 v[22:25], v[160:163], v[176:179], v[22:25]
	v_mfma_f32_16x16x32_bf16 v[78:81], v[146:149], v[184:187], v[78:81]
	v_mfma_f32_16x16x32_bf16 v[14:17], v[160:163], v[184:187], v[14:17]
	v_mfma_f32_16x16x32_bf16 v[70:73], v[146:149], v[200:203], v[70:73]
	v_mfma_f32_16x16x32_bf16 v[6:9], v[160:163], v[200:203], v[6:9]
	v_mfma_f32_16x16x32_bf16 v[90:93], v[156:159], v[172:175], v[90:93]
	v_mfma_f32_16x16x32_bf16 v[26:29], v[164:167], v[172:175], v[26:29]
	v_mfma_f32_16x16x32_bf16 v[86:89], v[156:159], v[180:183], v[86:89]
	v_mfma_f32_16x16x32_bf16 v[22:25], v[164:167], v[180:183], v[22:25]
	v_mfma_f32_16x16x32_bf16 v[78:81], v[156:159], v[188:191], v[78:81]
	v_mfma_f32_16x16x32_bf16 v[14:17], v[164:167], v[188:191], v[14:17]
	v_mfma_f32_16x16x32_bf16 v[70:73], v[156:159], v[204:207], v[70:73]
	v_mfma_f32_16x16x32_bf16 v[6:9], v[164:167], v[204:207], v[6:9]
	s_barrier
	s_setprio 0
	s_add_i32 s84, 0, 0x18000
	s_add_i32 s85, 0, 0x1c000
	v_add_u32_e32 v138, s84, v194
	v_add_u32_e32 v164, s85, v194
	ds_read_b128 v[114:117], v138
	ds_read_b128 v[118:121], v138 offset:1024
	ds_read_b128 v[130:133], v138 offset:2048
	ds_read_b128 v[138:141], v138 offset:3072
	ds_read_b128 v[146:149], v164
	ds_read_b128 v[156:159], v164 offset:1024
	ds_read_b128 v[160:163], v164 offset:2048
	ds_read_b128 v[164:167], v164 offset:3072
	s_add_u32 s68, s68, 0x80000
	s_addc_u32 s69, s69, 0
	s_mov_b32 m0, s5
	v_lshl_add_u64 v[216:217], s[68:69], 0, v[0:1]
	ds_read_b128 v[168:171], v199 offset:32768
	ds_read_b128 v[172:175], v199 offset:33792
	ds_read_b128 v[176:179], v199 offset:34816
	ds_read_b128 v[180:183], v199 offset:35840
	ds_read_b128 v[184:187], v199 offset:36864
	ds_read_b128 v[188:191], v199 offset:37888
	ds_read_b128 v[200:203], v199 offset:38912
	ds_read_b128 v[204:207], v199 offset:39936
	global_load_lds_dwordx4 v[216:217], off
	v_lshl_add_u64 v[216:217], s[68:69], 0, v[150:151]
	s_mov_b32 m0, s6
	s_nop 0
	global_load_lds_dwordx4 v[216:217], off
	s_waitcnt vmcnt(8)
	s_waitcnt lgkmcnt(0)
	s_setprio 1
	s_barrier
	v_mfma_f32_16x16x32_bf16 v[142:145], v[114:117], v[168:171], v[142:145]
	v_mfma_f32_16x16x32_bf16 v[62:65], v[130:133], v[168:171], v[62:65]
	v_mfma_f32_16x16x32_bf16 v[122:125], v[114:117], v[176:179], v[122:125]
	v_mfma_f32_16x16x32_bf16 v[50:53], v[130:133], v[176:179], v[50:53]
	v_mfma_f32_16x16x32_bf16 v[106:109], v[114:117], v[184:187], v[106:109]
	v_mfma_f32_16x16x32_bf16 v[42:45], v[130:133], v[184:187], v[42:45]
	v_mfma_f32_16x16x32_bf16 v[98:101], v[114:117], v[200:203], v[98:101]
	v_mfma_f32_16x16x32_bf16 v[34:37], v[130:133], v[200:203], v[34:37]
	v_mfma_f32_16x16x32_bf16 v[142:145], v[118:121], v[172:175], v[142:145]
	v_mfma_f32_16x16x32_bf16 v[62:65], v[138:141], v[172:175], v[62:65]
	v_mfma_f32_16x16x32_bf16 v[122:125], v[118:121], v[180:183], v[122:125]
	v_mfma_f32_16x16x32_bf16 v[50:53], v[138:141], v[180:183], v[50:53]
	v_mfma_f32_16x16x32_bf16 v[106:109], v[118:121], v[188:191], v[106:109]
	v_mfma_f32_16x16x32_bf16 v[42:45], v[138:141], v[188:191], v[42:45]
	v_mfma_f32_16x16x32_bf16 v[98:101], v[118:121], v[204:207], v[98:101]
	v_mfma_f32_16x16x32_bf16 v[34:37], v[138:141], v[204:207], v[34:37]
	v_mfma_f32_16x16x32_bf16 v[134:137], v[146:149], v[168:171], v[134:137]
	v_mfma_f32_16x16x32_bf16 v[58:61], v[160:163], v[168:171], v[58:61]
	v_mfma_f32_16x16x32_bf16 v[126:129], v[146:149], v[176:179], v[126:129]
	v_mfma_f32_16x16x32_bf16 v[54:57], v[160:163], v[176:179], v[54:57]
	v_mfma_f32_16x16x32_bf16 v[110:113], v[146:149], v[184:187], v[110:113]
	v_mfma_f32_16x16x32_bf16 v[46:49], v[160:163], v[184:187], v[46:49]
	v_mfma_f32_16x16x32_bf16 v[102:105], v[146:149], v[200:203], v[102:105]
	v_mfma_f32_16x16x32_bf16 v[38:41], v[160:163], v[200:203], v[38:41]
	v_mfma_f32_16x16x32_bf16 v[134:137], v[156:159], v[172:175], v[134:137]
	v_mfma_f32_16x16x32_bf16 v[58:61], v[164:167], v[172:175], v[58:61]
	v_mfma_f32_16x16x32_bf16 v[126:129], v[156:159], v[180:183], v[126:129]
	v_mfma_f32_16x16x32_bf16 v[54:57], v[164:167], v[180:183], v[54:57]
	v_mfma_f32_16x16x32_bf16 v[110:113], v[156:159], v[188:191], v[110:113]
	v_mfma_f32_16x16x32_bf16 v[46:49], v[164:167], v[188:191], v[46:49]
	v_mfma_f32_16x16x32_bf16 v[102:105], v[156:159], v[204:207], v[102:105]
	v_mfma_f32_16x16x32_bf16 v[38:41], v[164:167], v[204:207], v[38:41]
	s_barrier
; #define PG8_STAGE(bufoff, gbase, voff) do { _Pragma("unroll") for (int _i = 0; _i < 2; ++_i) \
;         __builtin_amdgcn_global_load_lds((const unsigned*)((const char*)(gbase) + (voff)[_i]), (PG8_LAS unsigned*)(lds + (bufoff) + ldsw + _i * 8192), 16, 0, 0); } while (0)
; #define PG8_LDA(dst, b, h) do { _Pragma("unroll") for (int m = 0; m < 4; ++m) _Pragma("unroll") for (int k = 0; k < 2; ++k) dst[m][k] = *(const PG8_LAS bf16x8*)(lds + PG8_SA(b, h) + aoff + m * 2048 + k * 1024); } while (0)
; #define PG8_MMA(ai, bj, At, Bt) do { __builtin_amdgcn_s_setprio(1); _Pragma("unroll") for (int m = 0; m < 4; ++m) _Pragma("unroll") for (int n = 0; n < 2; ++n) _Pragma("unroll") for (int k = 0; k < 2; ++k) \
;         acc[ai][bj][m][n] = __builtin_amdgcn_mfma_f32_16x16x32_bf16(Bt[n][k], At[m][k], acc[ai][bj][m][n], 0, 0, 0); __builtin_amdgcn_s_setprio(0); } while (0)
; #define PG8_WAIT_V(n) asm volatile("s_waitcnt vmcnt(" #n ")" ::: "memory")
; #define PG8_WAIT_L(n) asm volatile("s_waitcnt lgkmcnt(" #n ")" ::: "memory")
; #define PG8_BAR __builtin_amdgcn_s_barrier()
; #define PG8_SCHED __builtin_amdgcn_sched_barrier(0)
; template <class Epi, class Sched, bool ALIGN_EPI = false, bool SP2 = false>
; __device__ __forceinline__ void gemm_phase(PG8_LAS unsigned char* lds, const Gemm g, const Sched& S, const Epi& E) {
;     ...
;         for (int t = 0; t < nt; t += 2) {
;             const bool last = (t == nt - 2);
;             const char* a1 = cA + (size_t)(t + 1) * kstep;
;             const char* a2 = last ? nA : cA + (size_t)(t + 2) * kstep; const char* b2 = last ? nB : cB + (size_t)(t + 2) * kstep;
;             const char* a3 = a2 + kstep; const char* b3 = b2 + kstep;
;     ...
;             PG8_LDA(At, 1, 1); PG8_STAGE(PG8_SB(1, 0), b3, voffB); PG8_STAGE(PG8_SB(1, 1), b3 + hstep, voffB); PG8_STAGE(PG8_SA(1, 0), a3, voffA);
;             PG8_WAIT_V(8); PG8_WAIT_L(0); PG8_BAR; PG8_MMA(1, 0, At, B0); PG8_MMA(1, 1, At, B1); PG8_BAR; PG8_SCHED;
	s_setprio 0
	s_add_i32 s68, s84, s1
	v_lshl_add_u64 v[208:209], v[208:209], 0, s[34:35]
	s_mov_b32 m0, s68
	ds_read_b128 v[168:171], v199 offset:49152
	ds_read_b128 v[172:175], v199 offset:50176
	ds_read_b128 v[176:179], v199 offset:51200
	ds_read_b128 v[180:183], v199 offset:52224
	ds_read_b128 v[184:187], v199 offset:53248
	ds_read_b128 v[188:191], v199 offset:54272
	ds_read_b128 v[200:203], v199 offset:55296
	ds_read_b128 v[204:207], v199 offset:56320
	global_load_lds_dwordx4 v[208:209], off
	s_add_i32 m0, s68, 0x2000
	s_add_u32 s10, s10, 0x80080
	v_lshl_add_u64 v[208:209], v[210:211], 0, s[34:35]
	s_addc_u32 s11, s11, 0
	s_add_i32 s68, s85, s1
	global_load_lds_dwordx4 v[208:209], off
	v_lshl_add_u64 v[208:209], s[10:11], 0, v[0:1]
	s_mov_b32 m0, s68
	s_nop 0
	global_load_lds_dwordx4 v[208:209], off
	v_lshl_add_u64 v[208:209], s[10:11], 0, v[150:151]
	s_add_i32 m0, s68, 0x2000
	s_nop 0
	global_load_lds_dwordx4 v[208:209], off
	v_lshl_add_u64 v[208:209], v[212:213], 0, s[34:35]
	s_mov_b32 m0, s7
	s_nop 0
	global_load_lds_dwordx4 v[208:209], off
	v_lshl_add_u64 v[208:209], v[214:215], 0, s[34:35]
	s_mov_b32 m0, s30
	s_nop 0
	global_load_lds_dwordx4 v[208:209], off
	s_waitcnt vmcnt(8)
	s_waitcnt lgkmcnt(0)
	s_setprio 1
	s_barrier
	v_mfma_f32_16x16x32_bf16 v[94:97], v[114:117], v[168:171], v[94:97]
	v_mfma_f32_16x16x32_bf16 v[30:33], v[130:133], v[168:171], v[30:33]
	v_mfma_f32_16x16x32_bf16 v[82:85], v[114:117], v[176:179], v[82:85]
	v_mfma_f32_16x16x32_bf16 v[18:21], v[130:133], v[176:179], v[18:21]
	v_mfma_f32_16x16x32_bf16 v[74:77], v[114:117], v[184:187], v[74:77]
	v_mfma_f32_16x16x32_bf16 v[10:13], v[130:133], v[184:187], v[10:13]
	v_mfma_f32_16x16x32_bf16 v[66:69], v[114:117], v[200:203], v[66:69]
	v_mfma_f32_16x16x32_bf16 v[2:5], v[130:133], v[200:203], v[2:5]
	v_mfma_f32_16x16x32_bf16 v[94:97], v[118:121], v[172:175], v[94:97]
	v_mfma_f32_16x16x32_bf16 v[30:33], v[138:141], v[172:175], v[30:33]
	v_mfma_f32_16x16x32_bf16 v[82:85], v[118:121], v[180:183], v[82:85]
	v_mfma_f32_16x16x32_bf16 v[18:21], v[138:141], v[180:183], v[18:21]
	v_mfma_f32_16x16x32_bf16 v[74:77], v[118:121], v[188:191], v[74:77]
	v_mfma_f32_16x16x32_bf16 v[10:13], v[138:141], v[188:191], v[10:13]
	v_mfma_f32_16x16x32_bf16 v[66:69], v[118:121], v[204:207], v[66:69]
	v_mfma_f32_16x16x32_bf16 v[2:5], v[138:141], v[204:207], v[2:5]
	v_mfma_f32_16x16x32_bf16 v[90:93], v[146:149], v[168:171], v[90:93]
	v_mfma_f32_16x16x32_bf16 v[26:29], v[160:163], v[168:171], v[26:29]
	v_mfma_f32_16x16x32_bf16 v[86:89], v[146:149], v[176:179], v[86:89]
	v_mfma_f32_16x16x32_bf16 v[22:25], v[160:163], v[176:179], v[22:25]
	v_mfma_f32_16x16x32_bf16 v[78:81], v[146:149], v[184:187], v[78:81]
	v_mfma_f32_16x16x32_bf16 v[14:17], v[160:163], v[184:187], v[14:17]
	v_mfma_f32_16x16x32_bf16 v[70:73], v[146:149], v[200:203], v[70:73]
	v_mfma_f32_16x16x32_bf16 v[6:9], v[160:163], v[200:203], v[6:9]
	v_mfma_f32_16x16x32_bf16 v[90:93], v[156:159], v[172:175], v[90:93]
	v_mfma_f32_16x16x32_bf16 v[26:29], v[164:167], v[172:175], v[26:29]
	v_mfma_f32_16x16x32_bf16 v[86:89], v[156:159], v[180:183], v[86:89]
	v_mfma_f32_16x16x32_bf16 v[22:25], v[164:167], v[180:183], v[22:25]
	v_mfma_f32_16x16x32_bf16 v[78:81], v[156:159], v[188:191], v[78:81]
	v_mfma_f32_16x16x32_bf16 v[14:17], v[164:167], v[188:191], v[14:17]
	v_mfma_f32_16x16x32_bf16 v[70:73], v[156:159], v[204:207], v[70:73]
	v_mfma_f32_16x16x32_bf16 v[6:9], v[164:167], v[204:207], v[6:9]
	s_barrier
	s_setprio 0
	s_add_i32 s13, s13, 2
	s_add_u32 vcc_lo, vcc_lo, 0x100
	s_addc_u32 vcc_hi, vcc_hi, 0
	s_add_u32 s21, s21, 0x100
	s_addc_u32 s12, s12, 0
	s_cmp_gt_u32 s13, 29
	s_cbranch_scc0 .LBB0_38
	s_and_b64 vcc, exec, s[58:59]
	s_cbranch_vccz .LBB0_41
	s_barrier

; #define PG8_STAGE(bufoff, gbase, voff) do { _Pragma("unroll") for (int _i = 0; _i < 2; ++_i) \
;         __builtin_amdgcn_global_load_lds((const unsigned*)((const char*)(gbase) + (voff)[_i]), (PG8_LAS unsigned*)(lds + (bufoff) + ldsw + _i * 8192), 16, 0, 0); } while (0)
; #define PG8_LDA(dst, b, h) do { _Pragma("unroll") for (int m = 0; m < 4; ++m) _Pragma("unroll") for (int k = 0; k < 2; ++k) dst[m][k] = *(const PG8_LAS bf16x8*)(lds + PG8_SA(b, h) + aoff + m * 2048 + k * 1024); } while (0)
; #define PG8_LDB(dst, b, h) do { _Pragma("unroll") for (int n = 0; n < 2; ++n) _Pragma("unroll") for (int k = 0; k < 2; ++k) dst[n][k] = *(const PG8_LAS bf16x8*)(lds + PG8_SB(b, h) + boff + n * 2048 + k * 1024); } while (0)
; #define PG8_MMA(ai, bj, At, Bt) do { __builtin_amdgcn_s_setprio(1); _Pragma("unroll") for (int m = 0; m < 4; ++m) _Pragma("unroll") for (int n = 0; n < 2; ++n) _Pragma("unroll") for (int k = 0; k < 2; ++k) \
;         acc[ai][bj][m][n] = __builtin_amdgcn_mfma_f32_16x16x32_bf16(Bt[n][k], At[m][k], acc[ai][bj][m][n], 0, 0, 0); __builtin_amdgcn_s_setprio(0); } while (0)
; #define PG8_WAIT_V(n) asm volatile("s_waitcnt vmcnt(" #n ")" ::: "memory")
; #define PG8_WAIT_L(n) asm volatile("s_waitcnt lgkmcnt(" #n ")" ::: "memory")
; #define PG8_BAR __builtin_amdgcn_s_barrier()
; #define PG8_SCHED __builtin_amdgcn_sched_barrier(0)
; template <class Epi, class Sched, bool ALIGN_EPI = false, bool SP2 = false>
; __device__ __forceinline__ void gemm_phase(PG8_LAS unsigned char* lds, const Gemm g, const Sched& S, const Epi& E) {
;     ...
;             PG8_LDB(B0, 0, 0); PG8_LDB(B1, 0, 1); PG8_SCHED; PG8_LDA(At, 0, 0); PG8_STAGE(PG8_SA(1, 1), a1 + hstep, voffA);
;             PG8_WAIT_V(8); PG8_WAIT_L(0); PG8_BAR; PG8_MMA(0, 0, At, B0); PG8_MMA(0, 1, At, B1); PG8_BAR; PG8_SCHED;
;             PG8_LDA(At, 0, 1); PG8_STAGE(PG8_SB(0, 0), b2, voffB); PG8_STAGE(PG8_SB(0, 1), b2 + hstep, voffB); PG8_STAGE(PG8_SA(0, 0), a2, voffA);
.LBB0_169:
	s_add_u32 s10, s16, 0xfff80080
	s_addc_u32 s11, s17, -1
	s_add_i32 s21, 0, 0x10000
	s_cmp_eq_u32 s13, 28
	s_cselect_b32 s57, s43, s11
	s_cselect_b32 s56, s47, s10
	v_add_u32_e32 v148, s21, v151
	s_cselect_b32 s11, s45, s12
	s_cselect_b32 s10, s60, s61
	s_add_i32 s64, 0, 0x14000
	ds_read_b128 v[140:143], v148
	ds_read_b128 v[144:147], v148 offset:1024
	ds_read_b128 v[154:157], v148 offset:2048
	ds_read_b128 v[158:161], v148 offset:3072
	v_add_u32_e32 v148, s64, v151
	ds_read_b128 v[162:165], v148
	ds_read_b128 v[166:169], v148 offset:1024
	ds_read_b128 v[170:173], v148 offset:2048
	ds_read_b128 v[174:177], v148 offset:3072
	v_lshl_add_u64 v[210:211], s[16:17], 0, v[136:137]
	s_add_i32 m0, s2, 0xc000
	ds_read_b128 v[178:181], v153
	ds_read_b128 v[182:185], v153 offset:1024
	ds_read_b128 v[186:189], v153 offset:2048
	ds_read_b128 v[190:193], v153 offset:3072
	ds_read_b128 v[194:197], v153 offset:4096
	ds_read_b128 v[198:201], v153 offset:5120
	ds_read_b128 v[202:205], v153 offset:6144
	ds_read_b128 v[206:209], v153 offset:7168
	global_load_lds_dwordx4 v[210:211], off
	v_lshl_add_u64 v[210:211], s[16:17], 0, v[138:139]
	s_add_i32 m0, s2, 0xe000
	s_nop 0
	global_load_lds_dwordx4 v[210:211], off
	s_waitcnt vmcnt(8)
	s_waitcnt lgkmcnt(0)
	s_setprio 1
	s_barrier
	v_mfma_f32_16x16x32_bf16 v[126:129], v[140:143], v[178:181], v[126:129]
	v_mfma_f32_16x16x32_bf16 v[122:125], v[154:157], v[178:181], v[122:125]
	v_mfma_f32_16x16x32_bf16 v[110:113], v[140:143], v[186:189], v[110:113]
	v_mfma_f32_16x16x32_bf16 v[106:109], v[154:157], v[186:189], v[106:109]
	v_mfma_f32_16x16x32_bf16 v[94:97], v[140:143], v[194:197], v[94:97]
	v_mfma_f32_16x16x32_bf16 v[90:93], v[154:157], v[194:197], v[90:93]
	v_mfma_f32_16x16x32_bf16 v[78:81], v[140:143], v[202:205], v[78:81]
	v_mfma_f32_16x16x32_bf16 v[74:77], v[154:157], v[202:205], v[74:77]
	v_mfma_f32_16x16x32_bf16 v[126:129], v[144:147], v[182:185], v[126:129]
	v_mfma_f32_16x16x32_bf16 v[122:125], v[158:161], v[182:185], v[122:125]
	v_mfma_f32_16x16x32_bf16 v[110:113], v[144:147], v[190:193], v[110:113]
	v_mfma_f32_16x16x32_bf16 v[106:109], v[158:161], v[190:193], v[106:109]
	v_mfma_f32_16x16x32_bf16 v[94:97], v[144:147], v[198:201], v[94:97]
	v_mfma_f32_16x16x32_bf16 v[90:93], v[158:161], v[198:201], v[90:93]
	v_mfma_f32_16x16x32_bf16 v[78:81], v[144:147], v[206:209], v[78:81]
	v_mfma_f32_16x16x32_bf16 v[74:77], v[158:161], v[206:209], v[74:77]
	v_mfma_f32_16x16x32_bf16 v[118:121], v[162:165], v[178:181], v[118:121]
	v_mfma_f32_16x16x32_bf16 v[114:117], v[170:173], v[178:181], v[114:117]
	v_mfma_f32_16x16x32_bf16 v[102:105], v[162:165], v[186:189], v[102:105]
	v_mfma_f32_16x16x32_bf16 v[98:101], v[170:173], v[186:189], v[98:101]
	v_mfma_f32_16x16x32_bf16 v[86:89], v[162:165], v[194:197], v[86:89]
	v_mfma_f32_16x16x32_bf16 v[82:85], v[170:173], v[194:197], v[82:85]
	v_mfma_f32_16x16x32_bf16 v[70:73], v[162:165], v[202:205], v[70:73]
	v_mfma_f32_16x16x32_bf16 v[66:69], v[170:173], v[202:205], v[66:69]
	v_mfma_f32_16x16x32_bf16 v[118:121], v[166:169], v[182:185], v[118:121]
	v_mfma_f32_16x16x32_bf16 v[114:117], v[174:177], v[182:185], v[114:117]
	v_mfma_f32_16x16x32_bf16 v[102:105], v[166:169], v[190:193], v[102:105]
	v_mfma_f32_16x16x32_bf16 v[98:101], v[174:177], v[190:193], v[98:101]
	v_mfma_f32_16x16x32_bf16 v[86:89], v[166:169], v[198:201], v[86:89]
	v_mfma_f32_16x16x32_bf16 v[82:85], v[174:177], v[198:201], v[82:85]
	v_mfma_f32_16x16x32_bf16 v[70:73], v[166:169], v[206:209], v[70:73]
	v_mfma_f32_16x16x32_bf16 v[66:69], v[174:177], v[206:209], v[66:69]
	s_barrier
	s_setprio 0
	s_add_i32 s21, s21, s1
	v_lshl_add_u64 v[210:211], s[10:11], 0, v[0:1]
	s_mov_b32 m0, s21
	ds_read_b128 v[178:181], v153 offset:16384
	ds_read_b128 v[182:185], v153 offset:17408
	ds_read_b128 v[186:189], v153 offset:18432
	ds_read_b128 v[190:193], v153 offset:19456
	ds_read_b128 v[194:197], v153 offset:20480
	ds_read_b128 v[198:201], v153 offset:21504
	ds_read_b128 v[202:205], v153 offset:22528
	ds_read_b128 v[206:209], v153 offset:23552
	global_load_lds_dwordx4 v[210:211], off
	s_add_i32 m0, s21, 0x2000
	s_add_u32 s62, s10, 0x80000
	v_lshl_add_u64 v[212:213], s[10:11], 0, v[134:135]
	s_addc_u32 s63, s11, 0
	s_add_i32 s21, s64, s1
	global_load_lds_dwordx4 v[212:213], off
	v_lshl_add_u64 v[214:215], s[62:63], 0, v[0:1]
	s_mov_b32 m0, s21
	v_lshl_add_u64 v[216:217], s[56:57], 0, v[132:133]
	global_load_lds_dwordx4 v[214:215], off
	v_lshl_add_u64 v[214:215], s[62:63], 0, v[134:135]
	s_add_i32 m0, s21, 0x2000
	s_nop 0
	global_load_lds_dwordx4 v[214:215], off
	v_lshl_add_u64 v[214:215], s[56:57], 0, v[130:131]
	s_mov_b32 m0, s2
	s_nop 0
	global_load_lds_dwordx4 v[214:215], off
	s_mov_b32 m0, s4
	s_nop 0
	global_load_lds_dwordx4 v[216:217], off
	s_waitcnt vmcnt(8)
	s_waitcnt lgkmcnt(0)
	s_setprio 1
	s_barrier
; #define PG8_STAGE(bufoff, gbase, voff) do { _Pragma("unroll") for (int _i = 0; _i < 2; ++_i) \
;         __builtin_amdgcn_global_load_lds((const unsigned*)((const char*)(gbase) + (voff)[_i]), (PG8_LAS unsigned*)(lds + (bufoff) + ldsw + _i * 8192), 16, 0, 0); } while (0)
; #define PG8_LDA(dst, b, h) do { _Pragma("unroll") for (int m = 0; m < 4; ++m) _Pragma("unroll") for (int k = 0; k < 2; ++k) dst[m][k] = *(const PG8_LAS bf16x8*)(lds + PG8_SA(b, h) + aoff + m * 2048 + k * 1024); } while (0)
; #define PG8_LDB(dst, b, h) do { _Pragma("unroll") for (int n = 0; n < 2; ++n) _Pragma("unroll") for (int k = 0; k < 2; ++k) dst[n][k] = *(const PG8_LAS bf16x8*)(lds + PG8_SB(b, h) + boff + n * 2048 + k * 1024); } while (0)
; #define PG8_MMA(ai, bj, At, Bt) do { __builtin_amdgcn_s_setprio(1); _Pragma("unroll") for (int m = 0; m < 4; ++m) _Pragma("unroll") for (int n = 0; n < 2; ++n) _Pragma("unroll") for (int k = 0; k < 2; ++k) \
;         acc[ai][bj][m][n] = __builtin_amdgcn_mfma_f32_16x16x32_bf16(Bt[n][k], At[m][k], acc[ai][bj][m][n], 0, 0, 0); __builtin_amdgcn_s_setprio(0); } while (0)
; #define PG8_WAIT_V(n) asm volatile("s_waitcnt vmcnt(" #n ")" ::: "memory")
; #define PG8_WAIT_L(n) asm volatile("s_waitcnt lgkmcnt(" #n ")" ::: "memory")
; #define PG8_BAR __builtin_amdgcn_s_barrier()
; #define PG8_SCHED __builtin_amdgcn_sched_barrier(0)
; template <class Epi, class Sched, bool ALIGN_EPI = false, bool SP2 = false>
; __device__ __forceinline__ void gemm_phase(PG8_LAS unsigned char* lds, const Gemm g, const Sched& S, const Epi& E) {
;     ...
;             PG8_WAIT_V(8); PG8_WAIT_L(0); PG8_BAR; PG8_MMA(1, 0, At, B0); PG8_MMA(1, 1, At, B1); PG8_BAR; PG8_SCHED;
;             PG8_LDB(B0, 1, 0); PG8_LDB(B1, 1, 1); PG8_SCHED; PG8_LDA(At, 1, 0); PG8_STAGE(PG8_SA(0, 1), a2 + hstep, voffA);
;             PG8_WAIT_V(8); PG8_WAIT_L(0); PG8_BAR; PG8_MMA(0, 0, At, B0); PG8_MMA(0, 1, At, B1); PG8_BAR; PG8_SCHED;
	v_mfma_f32_16x16x32_bf16 v[62:65], v[140:143], v[178:181], v[62:65]
	v_mfma_f32_16x16x32_bf16 v[58:61], v[154:157], v[178:181], v[58:61]
	v_mfma_f32_16x16x32_bf16 v[46:49], v[140:143], v[186:189], v[46:49]
	v_mfma_f32_16x16x32_bf16 v[42:45], v[154:157], v[186:189], v[42:45]
	v_mfma_f32_16x16x32_bf16 v[30:33], v[140:143], v[194:197], v[30:33]
	v_mfma_f32_16x16x32_bf16 v[26:29], v[154:157], v[194:197], v[26:29]
	v_mfma_f32_16x16x32_bf16 v[14:17], v[140:143], v[202:205], v[14:17]
	v_mfma_f32_16x16x32_bf16 v[10:13], v[154:157], v[202:205], v[10:13]
	v_mfma_f32_16x16x32_bf16 v[62:65], v[144:147], v[182:185], v[62:65]
	v_mfma_f32_16x16x32_bf16 v[58:61], v[158:161], v[182:185], v[58:61]
	v_mfma_f32_16x16x32_bf16 v[46:49], v[144:147], v[190:193], v[46:49]
	v_mfma_f32_16x16x32_bf16 v[42:45], v[158:161], v[190:193], v[42:45]
	v_mfma_f32_16x16x32_bf16 v[30:33], v[144:147], v[198:201], v[30:33]
	v_mfma_f32_16x16x32_bf16 v[26:29], v[158:161], v[198:201], v[26:29]
	v_mfma_f32_16x16x32_bf16 v[14:17], v[144:147], v[206:209], v[14:17]
	v_mfma_f32_16x16x32_bf16 v[10:13], v[158:161], v[206:209], v[10:13]
	v_mfma_f32_16x16x32_bf16 v[54:57], v[162:165], v[178:181], v[54:57]
	v_mfma_f32_16x16x32_bf16 v[50:53], v[170:173], v[178:181], v[50:53]
	v_mfma_f32_16x16x32_bf16 v[38:41], v[162:165], v[186:189], v[38:41]
	v_mfma_f32_16x16x32_bf16 v[34:37], v[170:173], v[186:189], v[34:37]
	v_mfma_f32_16x16x32_bf16 v[22:25], v[162:165], v[194:197], v[22:25]
	v_mfma_f32_16x16x32_bf16 v[18:21], v[170:173], v[194:197], v[18:21]
	v_mfma_f32_16x16x32_bf16 v[6:9], v[162:165], v[202:205], v[6:9]
	v_mfma_f32_16x16x32_bf16 v[2:5], v[170:173], v[202:205], v[2:5]
	v_mfma_f32_16x16x32_bf16 v[54:57], v[166:169], v[182:185], v[54:57]
	v_mfma_f32_16x16x32_bf16 v[50:53], v[174:177], v[182:185], v[50:53]
	v_mfma_f32_16x16x32_bf16 v[38:41], v[166:169], v[190:193], v[38:41]
	v_mfma_f32_16x16x32_bf16 v[34:37], v[174:177], v[190:193], v[34:37]
	v_mfma_f32_16x16x32_bf16 v[22:25], v[166:169], v[198:201], v[22:25]
	v_mfma_f32_16x16x32_bf16 v[18:21], v[174:177], v[198:201], v[18:21]
	v_mfma_f32_16x16x32_bf16 v[6:9], v[166:169], v[206:209], v[6:9]
	v_mfma_f32_16x16x32_bf16 v[2:5], v[174:177], v[206:209], v[2:5]
	s_barrier
	s_setprio 0
	s_add_i32 s21, 0, 0x18000
	v_add_u32_e32 v148, s21, v151
	s_add_i32 s62, 0, 0x1c000
	ds_read_b128 v[140:143], v148
	ds_read_b128 v[144:147], v148 offset:1024
	ds_read_b128 v[154:157], v148 offset:2048
	ds_read_b128 v[158:161], v148 offset:3072
	v_add_u32_e32 v148, s62, v151
	ds_read_b128 v[162:165], v148
	ds_read_b128 v[166:169], v148 offset:1024
	ds_read_b128 v[170:173], v148 offset:2048
	ds_read_b128 v[174:177], v148 offset:3072
	s_add_u32 s56, s56, 0x80000
	s_addc_u32 s57, s57, 0
	s_mov_b32 m0, s5
	v_lshl_add_u64 v[222:223], s[56:57], 0, v[130:131]
	ds_read_b128 v[178:181], v153 offset:32768
	ds_read_b128 v[182:185], v153 offset:33792
	ds_read_b128 v[186:189], v153 offset:34816
	ds_read_b128 v[190:193], v153 offset:35840
	ds_read_b128 v[194:197], v153 offset:36864
	ds_read_b128 v[198:201], v153 offset:37888
	ds_read_b128 v[202:205], v153 offset:38912
	ds_read_b128 v[206:209], v153 offset:39936
	global_load_lds_dwordx4 v[222:223], off
	v_lshl_add_u64 v[222:223], s[56:57], 0, v[132:133]
	s_mov_b32 m0, s6
	s_nop 0
	global_load_lds_dwordx4 v[222:223], off
	s_waitcnt vmcnt(8)
	s_waitcnt lgkmcnt(0)
	s_setprio 1
	s_barrier
	v_mfma_f32_16x16x32_bf16 v[126:129], v[140:143], v[178:181], v[126:129]
	v_mfma_f32_16x16x32_bf16 v[122:125], v[154:157], v[178:181], v[122:125]
	v_mfma_f32_16x16x32_bf16 v[110:113], v[140:143], v[186:189], v[110:113]
	v_mfma_f32_16x16x32_bf16 v[106:109], v[154:157], v[186:189], v[106:109]
	v_mfma_f32_16x16x32_bf16 v[94:97], v[140:143], v[194:197], v[94:97]
	v_mfma_f32_16x16x32_bf16 v[90:93], v[154:157], v[194:197], v[90:93]
	v_mfma_f32_16x16x32_bf16 v[78:81], v[140:143], v[202:205], v[78:81]
	v_mfma_f32_16x16x32_bf16 v[74:77], v[154:157], v[202:205], v[74:77]
	v_mfma_f32_16x16x32_bf16 v[126:129], v[144:147], v[182:185], v[126:129]
	v_mfma_f32_16x16x32_bf16 v[122:125], v[158:161], v[182:185], v[122:125]
	v_mfma_f32_16x16x32_bf16 v[110:113], v[144:147], v[190:193], v[110:113]
	v_mfma_f32_16x16x32_bf16 v[106:109], v[158:161], v[190:193], v[106:109]
	v_mfma_f32_16x16x32_bf16 v[94:97], v[144:147], v[198:201], v[94:97]
	v_mfma_f32_16x16x32_bf16 v[90:93], v[158:161], v[198:201], v[90:93]
	v_mfma_f32_16x16x32_bf16 v[78:81], v[144:147], v[206:209], v[78:81]
	v_mfma_f32_16x16x32_bf16 v[74:77], v[158:161], v[206:209], v[74:77]
	v_mfma_f32_16x16x32_bf16 v[118:121], v[162:165], v[178:181], v[118:121]
	v_mfma_f32_16x16x32_bf16 v[114:117], v[170:173], v[178:181], v[114:117]
	v_mfma_f32_16x16x32_bf16 v[102:105], v[162:165], v[186:189], v[102:105]
	v_mfma_f32_16x16x32_bf16 v[98:101], v[170:173], v[186:189], v[98:101]
	v_mfma_f32_16x16x32_bf16 v[86:89], v[162:165], v[194:197], v[86:89]
	v_mfma_f32_16x16x32_bf16 v[82:85], v[170:173], v[194:197], v[82:85]
	v_mfma_f32_16x16x32_bf16 v[70:73], v[162:165], v[202:205], v[70:73]
	v_mfma_f32_16x16x32_bf16 v[66:69], v[170:173], v[202:205], v[66:69]
	v_mfma_f32_16x16x32_bf16 v[118:121], v[166:169], v[182:185], v[118:121]
	v_mfma_f32_16x16x32_bf16 v[114:117], v[174:177], v[182:185], v[114:117]
	v_mfma_f32_16x16x32_bf16 v[102:105], v[166:169], v[190:193], v[102:105]
	v_mfma_f32_16x16x32_bf16 v[98:101], v[174:177], v[190:193], v[98:101]
	v_mfma_f32_16x16x32_bf16 v[86:89], v[166:169], v[198:201], v[86:89]
	v_mfma_f32_16x16x32_bf16 v[82:85], v[174:177], v[198:201], v[82:85]
	v_mfma_f32_16x16x32_bf16 v[70:73], v[166:169], v[206:209], v[70:73]
	v_mfma_f32_16x16x32_bf16 v[66:69], v[174:177], v[206:209], v[66:69]
	s_barrier
; #define PG8_STAGE(bufoff, gbase, voff) do { _Pragma("unroll") for (int _i = 0; _i < 2; ++_i) \
;         __builtin_amdgcn_global_load_lds((const unsigned*)((const char*)(gbase) + (voff)[_i]), (PG8_LAS unsigned*)(lds + (bufoff) + ldsw + _i * 8192), 16, 0, 0); } while (0)
; #define PG8_LDA(dst, b, h) do { _Pragma("unroll") for (int m = 0; m < 4; ++m) _Pragma("unroll") for (int k = 0; k < 2; ++k) dst[m][k] = *(const PG8_LAS bf16x8*)(lds + PG8_SA(b, h) + aoff + m * 2048 + k * 1024); } while (0)
; #define PG8_MMA(ai, bj, At, Bt) do { __builtin_amdgcn_s_setprio(1); _Pragma("unroll") for (int m = 0; m < 4; ++m) _Pragma("unroll") for (int n = 0; n < 2; ++n) _Pragma("unroll") for (int k = 0; k < 2; ++k) \
;         acc[ai][bj][m][n] = __builtin_amdgcn_mfma_f32_16x16x32_bf16(Bt[n][k], At[m][k], acc[ai][bj][m][n], 0, 0, 0); __builtin_amdgcn_s_setprio(0); } while (0)
; #define PG8_WAIT_V(n) asm volatile("s_waitcnt vmcnt(" #n ")" ::: "memory")
; #define PG8_WAIT_L(n) asm volatile("s_waitcnt lgkmcnt(" #n ")" ::: "memory")
; #define PG8_BAR __builtin_amdgcn_s_barrier()
; #define PG8_SCHED __builtin_amdgcn_sched_barrier(0)
; template <class Epi, class Sched, bool ALIGN_EPI = false, bool SP2 = false>
; __device__ __forceinline__ void gemm_phase(PG8_LAS unsigned char* lds, const Gemm g, const Sched& S, const Epi& E) {
;     ...
;         for (int t = 0; t < nt; t += 2) {
;             const bool last = (t == nt - 2);
;             const char* a1 = cA + (size_t)(t + 1) * kstep;
;             const char* a2 = last ? nA : cA + (size_t)(t + 2) * kstep; const char* b2 = last ? nB : cB + (size_t)(t + 2) * kstep;
;             const char* a3 = a2 + kstep; const char* b3 = b2 + kstep;
;     ...
;             PG8_LDA(At, 1, 1); PG8_STAGE(PG8_SB(1, 0), b3, voffB); PG8_STAGE(PG8_SB(1, 1), b3 + hstep, voffB); PG8_STAGE(PG8_SA(1, 0), a3, voffA);
;             PG8_WAIT_V(8); PG8_WAIT_L(0); PG8_BAR; PG8_MMA(1, 0, At, B0); PG8_MMA(1, 1, At, B1); PG8_BAR; PG8_SCHED;
	s_setprio 0
	s_add_i32 s21, s21, s1
	v_lshl_add_u64 v[210:211], v[210:211], 0, s[34:35]
	s_mov_b32 m0, s21
	ds_read_b128 v[178:181], v153 offset:49152
	ds_read_b128 v[182:185], v153 offset:50176
	ds_read_b128 v[186:189], v153 offset:51200
	ds_read_b128 v[190:193], v153 offset:52224
	ds_read_b128 v[194:197], v153 offset:53248
	ds_read_b128 v[198:201], v153 offset:54272
	ds_read_b128 v[202:205], v153 offset:55296
	ds_read_b128 v[206:209], v153 offset:56320
	global_load_lds_dwordx4 v[210:211], off
	s_add_i32 m0, s21, 0x2000
	s_add_u32 s10, s10, 0x80080
	v_lshl_add_u64 v[210:211], v[212:213], 0, s[34:35]
	s_addc_u32 s11, s11, 0
	s_add_i32 s21, s62, s1
	global_load_lds_dwordx4 v[210:211], off
	v_lshl_add_u64 v[210:211], s[10:11], 0, v[0:1]
	s_mov_b32 m0, s21
	s_nop 0
	global_load_lds_dwordx4 v[210:211], off
	v_lshl_add_u64 v[210:211], s[10:11], 0, v[134:135]
	s_add_i32 m0, s21, 0x2000
	s_nop 0
	global_load_lds_dwordx4 v[210:211], off
	v_lshl_add_u64 v[210:211], v[214:215], 0, s[34:35]
	s_mov_b32 m0, s7
	s_nop 0
	global_load_lds_dwordx4 v[210:211], off
	v_lshl_add_u64 v[210:211], v[216:217], 0, s[34:35]
	s_mov_b32 m0, s30
	s_nop 0
	global_load_lds_dwordx4 v[210:211], off
	s_waitcnt vmcnt(8)
	s_waitcnt lgkmcnt(0)
	s_setprio 1
	s_barrier
	v_mfma_f32_16x16x32_bf16 v[62:65], v[140:143], v[178:181], v[62:65]
	v_mfma_f32_16x16x32_bf16 v[58:61], v[154:157], v[178:181], v[58:61]
	v_mfma_f32_16x16x32_bf16 v[46:49], v[140:143], v[186:189], v[46:49]
	v_mfma_f32_16x16x32_bf16 v[42:45], v[154:157], v[186:189], v[42:45]
	v_mfma_f32_16x16x32_bf16 v[30:33], v[140:143], v[194:197], v[30:33]
	v_mfma_f32_16x16x32_bf16 v[26:29], v[154:157], v[194:197], v[26:29]
	v_mfma_f32_16x16x32_bf16 v[14:17], v[140:143], v[202:205], v[14:17]
	v_mfma_f32_16x16x32_bf16 v[10:13], v[154:157], v[202:205], v[10:13]
	v_mfma_f32_16x16x32_bf16 v[62:65], v[144:147], v[182:185], v[62:65]
	v_mfma_f32_16x16x32_bf16 v[58:61], v[158:161], v[182:185], v[58:61]
	v_mfma_f32_16x16x32_bf16 v[46:49], v[144:147], v[190:193], v[46:49]
	v_mfma_f32_16x16x32_bf16 v[42:45], v[158:161], v[190:193], v[42:45]
	v_mfma_f32_16x16x32_bf16 v[30:33], v[144:147], v[198:201], v[30:33]
	v_mfma_f32_16x16x32_bf16 v[26:29], v[158:161], v[198:201], v[26:29]
	v_mfma_f32_16x16x32_bf16 v[14:17], v[144:147], v[206:209], v[14:17]
	v_mfma_f32_16x16x32_bf16 v[10:13], v[158:161], v[206:209], v[10:13]
	v_mfma_f32_16x16x32_bf16 v[54:57], v[162:165], v[178:181], v[54:57]
	v_mfma_f32_16x16x32_bf16 v[50:53], v[170:173], v[178:181], v[50:53]
	v_mfma_f32_16x16x32_bf16 v[38:41], v[162:165], v[186:189], v[38:41]
	v_mfma_f32_16x16x32_bf16 v[34:37], v[170:173], v[186:189], v[34:37]
	v_mfma_f32_16x16x32_bf16 v[22:25], v[162:165], v[194:197], v[22:25]
	v_mfma_f32_16x16x32_bf16 v[18:21], v[170:173], v[194:197], v[18:21]
	v_mfma_f32_16x16x32_bf16 v[6:9], v[162:165], v[202:205], v[6:9]
	v_mfma_f32_16x16x32_bf16 v[2:5], v[170:173], v[202:205], v[2:5]
	v_mfma_f32_16x16x32_bf16 v[54:57], v[166:169], v[182:185], v[54:57]
	v_mfma_f32_16x16x32_bf16 v[50:53], v[174:177], v[182:185], v[50:53]
	v_mfma_f32_16x16x32_bf16 v[38:41], v[166:169], v[190:193], v[38:41]
	v_mfma_f32_16x16x32_bf16 v[34:37], v[174:177], v[190:193], v[34:37]
	v_mfma_f32_16x16x32_bf16 v[22:25], v[166:169], v[198:201], v[22:25]
	v_mfma_f32_16x16x32_bf16 v[18:21], v[174:177], v[198:201], v[18:21]
	v_mfma_f32_16x16x32_bf16 v[6:9], v[166:169], v[206:209], v[6:9]
	v_mfma_f32_16x16x32_bf16 v[2:5], v[174:177], v[206:209], v[2:5]
	s_barrier
	s_setprio 0
	s_add_i32 s13, s13, 2
	s_add_u32 s16, s16, 0x100
	s_addc_u32 s17, s17, 0
	s_add_u32 s61, s61, 0x100
	s_addc_u32 s12, s12, 0
	s_cmp_gt_u32 s13, 29
	s_cbranch_scc0 .LBB0_169
	s_and_b64 vcc, exec, s[22:23]
	s_cbranch_vccz .LBB0_172
	s_barrier

; #define PG8_STAGE(bufoff, gbase, voff) do { _Pragma("unroll") for (int _i = 0; _i < 2; ++_i) \
;         __builtin_amdgcn_global_load_lds((const unsigned*)((const char*)(gbase) + (voff)[_i]), (PG8_LAS unsigned*)(lds + (bufoff) + ldsw + _i * 8192), 16, 0, 0); } while (0)
; #define PG8_LDA(dst, b, h) do { _Pragma("unroll") for (int m = 0; m < 4; ++m) _Pragma("unroll") for (int k = 0; k < 2; ++k) dst[m][k] = *(const PG8_LAS bf16x8*)(lds + PG8_SA(b, h) + aoff + m * 2048 + k * 1024); } while (0)
; #define PG8_LDB(dst, b, h) do { _Pragma("unroll") for (int n = 0; n < 2; ++n) _Pragma("unroll") for (int k = 0; k < 2; ++k) dst[n][k] = *(const PG8_LAS bf16x8*)(lds + PG8_SB(b, h) + boff + n * 2048 + k * 1024); } while (0)
; #define PG8_MMA(ai, bj, At, Bt) do { __builtin_amdgcn_s_setprio(1); _Pragma("unroll") for (int m = 0; m < 4; ++m) _Pragma("unroll") for (int n = 0; n < 2; ++n) _Pragma("unroll") for (int k = 0; k < 2; ++k) \
;         acc[ai][bj][m][n] = __builtin_amdgcn_mfma_f32_16x16x32_bf16(Bt[n][k], At[m][k], acc[ai][bj][m][n], 0, 0, 0); __builtin_amdgcn_s_setprio(0); } while (0)
; #define PG8_WAIT_V(n) asm volatile("s_waitcnt vmcnt(" #n ")" ::: "memory")
; #define PG8_WAIT_L(n) asm volatile("s_waitcnt lgkmcnt(" #n ")" ::: "memory")
; #define PG8_BAR __builtin_amdgcn_s_barrier()
; #define PG8_SCHED __builtin_amdgcn_sched_barrier(0)
; template <class Epi, class Sched, bool ALIGN_EPI = false, bool SP2 = false>
; __device__ __forceinline__ void gemm_phase(PG8_LAS unsigned char* lds, const Gemm g, const Sched& S, const Epi& E) {
;     ...
;             PG8_LDB(B0, 0, 0); PG8_LDB(B1, 0, 1); PG8_SCHED; PG8_LDA(At, 0, 0); PG8_STAGE(PG8_SA(1, 1), a1 + hstep, voffA);
;             PG8_WAIT_V(8); PG8_WAIT_L(0); PG8_BAR; PG8_MMA(0, 0, At, B0); PG8_MMA(0, 1, At, B1); PG8_BAR; PG8_SCHED;
;             PG8_LDA(At, 0, 1); PG8_STAGE(PG8_SB(0, 0), b2, voffB); PG8_STAGE(PG8_SB(0, 1), b2 + hstep, voffB); PG8_STAGE(PG8_SA(0, 0), a2, voffA);
.LBB0_223:
	s_add_i32 s14, s10, 2
	s_add_u32 s15, s8, 0x80
	s_addc_u32 s11, s9, 0
	s_add_i32 s64, 0, 0x10000
	s_cmp_eq_u32 s57, s10
	s_cselect_b32 s11, s51, s11
	s_cselect_b32 s10, s50, s15
	s_cselect_b32 s45, s53, s13
	s_cselect_b32 s44, s52, s12
	s_add_i32 s15, 0, 0x14000
	v_add_u32_e32 v156, s64, v145
	v_add_u32_e32 v172, s15, v145
	ds_read_b128 v[140:143], v156
	ds_read_b128 v[148:151], v156 offset:1024
	ds_read_b128 v[152:155], v156 offset:2048
	ds_read_b128 v[156:159], v156 offset:3072
	ds_read_b128 v[160:163], v172
	ds_read_b128 v[164:167], v172 offset:1024
	ds_read_b128 v[168:171], v172 offset:2048
	ds_read_b128 v[172:175], v172 offset:3072
	v_lshl_add_u64 v[208:209], s[8:9], 0, v[136:137]
	s_add_i32 m0, s21, 0xc000
	ds_read_b128 v[176:179], v147
	ds_read_b128 v[180:183], v147 offset:1024
	ds_read_b128 v[184:187], v147 offset:2048
	ds_read_b128 v[188:191], v147 offset:3072
	ds_read_b128 v[192:195], v147 offset:4096
	ds_read_b128 v[196:199], v147 offset:5120
	ds_read_b128 v[200:203], v147 offset:6144
	ds_read_b128 v[204:207], v147 offset:7168
	global_load_lds_dwordx4 v[208:209], off
	v_lshl_add_u64 v[208:209], s[8:9], 0, v[138:139]
	s_add_i32 m0, s21, 0xe000
	s_nop 0
	global_load_lds_dwordx4 v[208:209], off
	s_waitcnt vmcnt(8)
	s_waitcnt lgkmcnt(0)
	s_setprio 1
	s_barrier
	v_mfma_f32_16x16x32_bf16 v[126:129], v[140:143], v[176:179], v[126:129]
	v_mfma_f32_16x16x32_bf16 v[122:125], v[152:155], v[176:179], v[122:125]
	v_mfma_f32_16x16x32_bf16 v[110:113], v[140:143], v[184:187], v[110:113]
	v_mfma_f32_16x16x32_bf16 v[106:109], v[152:155], v[184:187], v[106:109]
	v_mfma_f32_16x16x32_bf16 v[94:97], v[140:143], v[192:195], v[94:97]
	v_mfma_f32_16x16x32_bf16 v[90:93], v[152:155], v[192:195], v[90:93]
	v_mfma_f32_16x16x32_bf16 v[78:81], v[140:143], v[200:203], v[78:81]
	v_mfma_f32_16x16x32_bf16 v[74:77], v[152:155], v[200:203], v[74:77]
	v_mfma_f32_16x16x32_bf16 v[126:129], v[148:151], v[180:183], v[126:129]
	v_mfma_f32_16x16x32_bf16 v[122:125], v[156:159], v[180:183], v[122:125]
	v_mfma_f32_16x16x32_bf16 v[110:113], v[148:151], v[188:191], v[110:113]
	v_mfma_f32_16x16x32_bf16 v[106:109], v[156:159], v[188:191], v[106:109]
	v_mfma_f32_16x16x32_bf16 v[94:97], v[148:151], v[196:199], v[94:97]
	v_mfma_f32_16x16x32_bf16 v[90:93], v[156:159], v[196:199], v[90:93]
	v_mfma_f32_16x16x32_bf16 v[78:81], v[148:151], v[204:207], v[78:81]
	v_mfma_f32_16x16x32_bf16 v[74:77], v[156:159], v[204:207], v[74:77]
	v_mfma_f32_16x16x32_bf16 v[118:121], v[160:163], v[176:179], v[118:121]
	v_mfma_f32_16x16x32_bf16 v[114:117], v[168:171], v[176:179], v[114:117]
	v_mfma_f32_16x16x32_bf16 v[102:105], v[160:163], v[184:187], v[102:105]
	v_mfma_f32_16x16x32_bf16 v[98:101], v[168:171], v[184:187], v[98:101]
	v_mfma_f32_16x16x32_bf16 v[86:89], v[160:163], v[192:195], v[86:89]
	v_mfma_f32_16x16x32_bf16 v[82:85], v[168:171], v[192:195], v[82:85]
	v_mfma_f32_16x16x32_bf16 v[70:73], v[160:163], v[200:203], v[70:73]
	v_mfma_f32_16x16x32_bf16 v[66:69], v[168:171], v[200:203], v[66:69]
	v_mfma_f32_16x16x32_bf16 v[118:121], v[164:167], v[180:183], v[118:121]
	v_mfma_f32_16x16x32_bf16 v[114:117], v[172:175], v[180:183], v[114:117]
	v_mfma_f32_16x16x32_bf16 v[102:105], v[164:167], v[188:191], v[102:105]
	v_mfma_f32_16x16x32_bf16 v[98:101], v[172:175], v[188:191], v[98:101]
	v_mfma_f32_16x16x32_bf16 v[86:89], v[164:167], v[196:199], v[86:89]
	v_mfma_f32_16x16x32_bf16 v[82:85], v[172:175], v[196:199], v[82:85]
	v_mfma_f32_16x16x32_bf16 v[70:73], v[164:167], v[204:207], v[70:73]
	v_mfma_f32_16x16x32_bf16 v[66:69], v[172:175], v[204:207], v[66:69]
	s_barrier
	s_setprio 0
	s_add_i32 s64, s64, s7
	v_lshl_add_u64 v[208:209], s[44:45], 0, v[0:1]
	s_mov_b32 m0, s64
	ds_read_b128 v[176:179], v147 offset:16384
	ds_read_b128 v[180:183], v147 offset:17408
	ds_read_b128 v[184:187], v147 offset:18432
	ds_read_b128 v[188:191], v147 offset:19456
	ds_read_b128 v[192:195], v147 offset:20480
	ds_read_b128 v[196:199], v147 offset:21504
	ds_read_b128 v[200:203], v147 offset:22528
	ds_read_b128 v[204:207], v147 offset:23552
	global_load_lds_dwordx4 v[208:209], off
	s_add_i32 m0, s64, 0x2000
	v_lshl_add_u64 v[210:211], s[44:45], 0, v[134:135]
	s_add_u32 s44, s44, s30
	s_addc_u32 s45, s45, 0
	s_add_i32 s15, s15, s7
	global_load_lds_dwordx4 v[210:211], off
	v_lshl_add_u64 v[212:213], s[44:45], 0, v[0:1]
	s_mov_b32 m0, s15
	v_lshl_add_u64 v[214:215], s[44:45], 0, v[134:135]
	global_load_lds_dwordx4 v[212:213], off
	s_add_i32 m0, s15, 0x2000
	v_lshl_add_u64 v[216:217], s[10:11], 0, v[130:131]
	global_load_lds_dwordx4 v[214:215], off
	s_mov_b32 m0, s21
	v_lshl_add_u64 v[222:223], s[10:11], 0, v[132:133]
	global_load_lds_dwordx4 v[216:217], off
	s_mov_b32 m0, s26
	s_nop 0
	global_load_lds_dwordx4 v[222:223], off
	s_waitcnt vmcnt(8)
	s_waitcnt lgkmcnt(0)
	s_setprio 1
	s_barrier
; #define PG8_STAGE(bufoff, gbase, voff) do { _Pragma("unroll") for (int _i = 0; _i < 2; ++_i) \
;         __builtin_amdgcn_global_load_lds((const unsigned*)((const char*)(gbase) + (voff)[_i]), (PG8_LAS unsigned*)(lds + (bufoff) + ldsw + _i * 8192), 16, 0, 0); } while (0)
; #define PG8_LDA(dst, b, h) do { _Pragma("unroll") for (int m = 0; m < 4; ++m) _Pragma("unroll") for (int k = 0; k < 2; ++k) dst[m][k] = *(const PG8_LAS bf16x8*)(lds + PG8_SA(b, h) + aoff + m * 2048 + k * 1024); } while (0)
; #define PG8_LDB(dst, b, h) do { _Pragma("unroll") for (int n = 0; n < 2; ++n) _Pragma("unroll") for (int k = 0; k < 2; ++k) dst[n][k] = *(const PG8_LAS bf16x8*)(lds + PG8_SB(b, h) + boff + n * 2048 + k * 1024); } while (0)
; #define PG8_MMA(ai, bj, At, Bt) do { __builtin_amdgcn_s_setprio(1); _Pragma("unroll") for (int m = 0; m < 4; ++m) _Pragma("unroll") for (int n = 0; n < 2; ++n) _Pragma("unroll") for (int k = 0; k < 2; ++k) \
;         acc[ai][bj][m][n] = __builtin_amdgcn_mfma_f32_16x16x32_bf16(Bt[n][k], At[m][k], acc[ai][bj][m][n], 0, 0, 0); __builtin_amdgcn_s_setprio(0); } while (0)
; #define PG8_WAIT_V(n) asm volatile("s_waitcnt vmcnt(" #n ")" ::: "memory")
; #define PG8_WAIT_L(n) asm volatile("s_waitcnt lgkmcnt(" #n ")" ::: "memory")
; #define PG8_BAR __builtin_amdgcn_s_barrier()
; #define PG8_SCHED __builtin_amdgcn_sched_barrier(0)
; template <class Epi, class Sched, bool ALIGN_EPI = false, bool SP2 = false>
; __device__ __forceinline__ void gemm_phase(PG8_LAS unsigned char* lds, const Gemm g, const Sched& S, const Epi& E) {
;     ...
;             PG8_WAIT_V(8); PG8_WAIT_L(0); PG8_BAR; PG8_MMA(1, 0, At, B0); PG8_MMA(1, 1, At, B1); PG8_BAR; PG8_SCHED;
;             PG8_LDB(B0, 1, 0); PG8_LDB(B1, 1, 1); PG8_SCHED; PG8_LDA(At, 1, 0); PG8_STAGE(PG8_SA(0, 1), a2 + hstep, voffA);
;             PG8_WAIT_V(8); PG8_WAIT_L(0); PG8_BAR; PG8_MMA(0, 0, At, B0); PG8_MMA(0, 1, At, B1); PG8_BAR; PG8_SCHED;
	v_mfma_f32_16x16x32_bf16 v[62:65], v[140:143], v[176:179], v[62:65]
	v_mfma_f32_16x16x32_bf16 v[58:61], v[152:155], v[176:179], v[58:61]
	v_mfma_f32_16x16x32_bf16 v[46:49], v[140:143], v[184:187], v[46:49]
	v_mfma_f32_16x16x32_bf16 v[42:45], v[152:155], v[184:187], v[42:45]
	v_mfma_f32_16x16x32_bf16 v[30:33], v[140:143], v[192:195], v[30:33]
	v_mfma_f32_16x16x32_bf16 v[26:29], v[152:155], v[192:195], v[26:29]
	v_mfma_f32_16x16x32_bf16 v[14:17], v[140:143], v[200:203], v[14:17]
	v_mfma_f32_16x16x32_bf16 v[10:13], v[152:155], v[200:203], v[10:13]
	v_mfma_f32_16x16x32_bf16 v[62:65], v[148:151], v[180:183], v[62:65]
	v_mfma_f32_16x16x32_bf16 v[58:61], v[156:159], v[180:183], v[58:61]
	v_mfma_f32_16x16x32_bf16 v[46:49], v[148:151], v[188:191], v[46:49]
	v_mfma_f32_16x16x32_bf16 v[42:45], v[156:159], v[188:191], v[42:45]
	v_mfma_f32_16x16x32_bf16 v[30:33], v[148:151], v[196:199], v[30:33]
	v_mfma_f32_16x16x32_bf16 v[26:29], v[156:159], v[196:199], v[26:29]
	v_mfma_f32_16x16x32_bf16 v[14:17], v[148:151], v[204:207], v[14:17]
	v_mfma_f32_16x16x32_bf16 v[10:13], v[156:159], v[204:207], v[10:13]
	v_mfma_f32_16x16x32_bf16 v[54:57], v[160:163], v[176:179], v[54:57]
	v_mfma_f32_16x16x32_bf16 v[50:53], v[168:171], v[176:179], v[50:53]
	v_mfma_f32_16x16x32_bf16 v[38:41], v[160:163], v[184:187], v[38:41]
	v_mfma_f32_16x16x32_bf16 v[34:37], v[168:171], v[184:187], v[34:37]
	v_mfma_f32_16x16x32_bf16 v[22:25], v[160:163], v[192:195], v[22:25]
	v_mfma_f32_16x16x32_bf16 v[18:21], v[168:171], v[192:195], v[18:21]
	v_mfma_f32_16x16x32_bf16 v[6:9], v[160:163], v[200:203], v[6:9]
	v_mfma_f32_16x16x32_bf16 v[2:5], v[168:171], v[200:203], v[2:5]
	v_mfma_f32_16x16x32_bf16 v[54:57], v[164:167], v[180:183], v[54:57]
	v_mfma_f32_16x16x32_bf16 v[50:53], v[172:175], v[180:183], v[50:53]
	v_mfma_f32_16x16x32_bf16 v[38:41], v[164:167], v[188:191], v[38:41]
	v_mfma_f32_16x16x32_bf16 v[34:37], v[172:175], v[188:191], v[34:37]
	v_mfma_f32_16x16x32_bf16 v[22:25], v[164:167], v[196:199], v[22:25]
	v_mfma_f32_16x16x32_bf16 v[18:21], v[172:175], v[196:199], v[18:21]
	v_mfma_f32_16x16x32_bf16 v[6:9], v[164:167], v[204:207], v[6:9]
	v_mfma_f32_16x16x32_bf16 v[2:5], v[172:175], v[204:207], v[2:5]
	s_barrier
	s_setprio 0
	s_add_i32 s15, 0, 0x18000
	s_add_i32 s44, 0, 0x1c000
	v_add_u32_e32 v156, s15, v145
	v_add_u32_e32 v172, s44, v145
	ds_read_b128 v[140:143], v156
	ds_read_b128 v[148:151], v156 offset:1024
	ds_read_b128 v[152:155], v156 offset:2048
	ds_read_b128 v[156:159], v156 offset:3072
	ds_read_b128 v[160:163], v172
	ds_read_b128 v[164:167], v172 offset:1024
	ds_read_b128 v[168:171], v172 offset:2048
	ds_read_b128 v[172:175], v172 offset:3072
	s_add_u32 s10, s10, s30
	s_addc_u32 s11, s11, 0
	s_mov_b32 m0, s27
	v_lshl_add_u64 v[224:225], s[10:11], 0, v[130:131]
	ds_read_b128 v[176:179], v147 offset:32768
	ds_read_b128 v[180:183], v147 offset:33792
	ds_read_b128 v[184:187], v147 offset:34816
	ds_read_b128 v[188:191], v147 offset:35840
	ds_read_b128 v[192:195], v147 offset:36864
	ds_read_b128 v[196:199], v147 offset:37888
	ds_read_b128 v[200:203], v147 offset:38912
	ds_read_b128 v[204:207], v147 offset:39936
	global_load_lds_dwordx4 v[224:225], off
	v_lshl_add_u64 v[224:225], s[10:11], 0, v[132:133]
	s_mov_b32 m0, s54
	s_nop 0
	global_load_lds_dwordx4 v[224:225], off
	s_waitcnt vmcnt(8)
	s_waitcnt lgkmcnt(0)
	s_setprio 1
	s_barrier
	v_mfma_f32_16x16x32_bf16 v[126:129], v[140:143], v[176:179], v[126:129]
	v_mfma_f32_16x16x32_bf16 v[122:125], v[152:155], v[176:179], v[122:125]
	v_mfma_f32_16x16x32_bf16 v[110:113], v[140:143], v[184:187], v[110:113]
	v_mfma_f32_16x16x32_bf16 v[106:109], v[152:155], v[184:187], v[106:109]
	v_mfma_f32_16x16x32_bf16 v[94:97], v[140:143], v[192:195], v[94:97]
	v_mfma_f32_16x16x32_bf16 v[90:93], v[152:155], v[192:195], v[90:93]
	v_mfma_f32_16x16x32_bf16 v[78:81], v[140:143], v[200:203], v[78:81]
	v_mfma_f32_16x16x32_bf16 v[74:77], v[152:155], v[200:203], v[74:77]
	v_mfma_f32_16x16x32_bf16 v[126:129], v[148:151], v[180:183], v[126:129]
	v_mfma_f32_16x16x32_bf16 v[122:125], v[156:159], v[180:183], v[122:125]
	v_mfma_f32_16x16x32_bf16 v[110:113], v[148:151], v[188:191], v[110:113]
	v_mfma_f32_16x16x32_bf16 v[106:109], v[156:159], v[188:191], v[106:109]
	v_mfma_f32_16x16x32_bf16 v[94:97], v[148:151], v[196:199], v[94:97]
	v_mfma_f32_16x16x32_bf16 v[90:93], v[156:159], v[196:199], v[90:93]
	v_mfma_f32_16x16x32_bf16 v[78:81], v[148:151], v[204:207], v[78:81]
	v_mfma_f32_16x16x32_bf16 v[74:77], v[156:159], v[204:207], v[74:77]
	v_mfma_f32_16x16x32_bf16 v[118:121], v[160:163], v[176:179], v[118:121]
	v_mfma_f32_16x16x32_bf16 v[114:117], v[168:171], v[176:179], v[114:117]
	v_mfma_f32_16x16x32_bf16 v[102:105], v[160:163], v[184:187], v[102:105]
	v_mfma_f32_16x16x32_bf16 v[98:101], v[168:171], v[184:187], v[98:101]
	v_mfma_f32_16x16x32_bf16 v[86:89], v[160:163], v[192:195], v[86:89]
	v_mfma_f32_16x16x32_bf16 v[82:85], v[168:171], v[192:195], v[82:85]
	v_mfma_f32_16x16x32_bf16 v[70:73], v[160:163], v[200:203], v[70:73]
	v_mfma_f32_16x16x32_bf16 v[66:69], v[168:171], v[200:203], v[66:69]
	v_mfma_f32_16x16x32_bf16 v[118:121], v[164:167], v[180:183], v[118:121]
	v_mfma_f32_16x16x32_bf16 v[114:117], v[172:175], v[180:183], v[114:117]
	v_mfma_f32_16x16x32_bf16 v[102:105], v[164:167], v[188:191], v[102:105]
	v_mfma_f32_16x16x32_bf16 v[98:101], v[172:175], v[188:191], v[98:101]
	v_mfma_f32_16x16x32_bf16 v[86:89], v[164:167], v[196:199], v[86:89]
	v_mfma_f32_16x16x32_bf16 v[82:85], v[172:175], v[196:199], v[82:85]
	v_mfma_f32_16x16x32_bf16 v[70:73], v[164:167], v[204:207], v[70:73]
	v_mfma_f32_16x16x32_bf16 v[66:69], v[172:175], v[204:207], v[66:69]
	s_barrier
; #define PG8_STAGE(bufoff, gbase, voff) do { _Pragma("unroll") for (int _i = 0; _i < 2; ++_i) \
;         __builtin_amdgcn_global_load_lds((const unsigned*)((const char*)(gbase) + (voff)[_i]), (PG8_LAS unsigned*)(lds + (bufoff) + ldsw + _i * 8192), 16, 0, 0); } while (0)
; #define PG8_LDA(dst, b, h) do { _Pragma("unroll") for (int m = 0; m < 4; ++m) _Pragma("unroll") for (int k = 0; k < 2; ++k) dst[m][k] = *(const PG8_LAS bf16x8*)(lds + PG8_SA(b, h) + aoff + m * 2048 + k * 1024); } while (0)
; #define PG8_MMA(ai, bj, At, Bt) do { __builtin_amdgcn_s_setprio(1); _Pragma("unroll") for (int m = 0; m < 4; ++m) _Pragma("unroll") for (int n = 0; n < 2; ++n) _Pragma("unroll") for (int k = 0; k < 2; ++k) \
;         acc[ai][bj][m][n] = __builtin_amdgcn_mfma_f32_16x16x32_bf16(Bt[n][k], At[m][k], acc[ai][bj][m][n], 0, 0, 0); __builtin_amdgcn_s_setprio(0); } while (0)
; #define PG8_WAIT_V(n) asm volatile("s_waitcnt vmcnt(" #n ")" ::: "memory")
; #define PG8_WAIT_L(n) asm volatile("s_waitcnt lgkmcnt(" #n ")" ::: "memory")
; #define PG8_BAR __builtin_amdgcn_s_barrier()
; #define PG8_SCHED __builtin_amdgcn_sched_barrier(0)
; template <class Epi, class Sched, bool ALIGN_EPI = false, bool SP2 = false>
; __device__ __forceinline__ void gemm_phase(PG8_LAS unsigned char* lds, const Gemm g, const Sched& S, const Epi& E) {
;     ...
;         for (int t = 0; t < nt; t += 2) {
;             const bool last = (t == nt - 2);
;             const char* a1 = cA + (size_t)(t + 1) * kstep;
;             const char* a2 = last ? nA : cA + (size_t)(t + 2) * kstep; const char* b2 = last ? nB : cB + (size_t)(t + 2) * kstep;
;             const char* a3 = a2 + kstep; const char* b3 = b2 + kstep;
;     ...
;             PG8_LDA(At, 1, 1); PG8_STAGE(PG8_SB(1, 0), b3, voffB); PG8_STAGE(PG8_SB(1, 1), b3 + hstep, voffB); PG8_STAGE(PG8_SA(1, 0), a3, voffA);
;             PG8_WAIT_V(8); PG8_WAIT_L(0); PG8_BAR; PG8_MMA(1, 0, At, B0); PG8_MMA(1, 1, At, B1); PG8_BAR; PG8_SCHED;
	s_setprio 0
	s_add_i32 s10, s15, s7
	v_lshl_add_u64 v[208:209], v[208:209], 0, s[34:35]
	s_mov_b32 m0, s10
	ds_read_b128 v[176:179], v147 offset:49152
	ds_read_b128 v[180:183], v147 offset:50176
	ds_read_b128 v[184:187], v147 offset:51200
	ds_read_b128 v[188:191], v147 offset:52224
	ds_read_b128 v[192:195], v147 offset:53248
	ds_read_b128 v[196:199], v147 offset:54272
	ds_read_b128 v[200:203], v147 offset:55296
	ds_read_b128 v[204:207], v147 offset:56320
	global_load_lds_dwordx4 v[208:209], off
	v_lshl_add_u64 v[208:209], v[210:211], 0, s[34:35]
	s_add_i32 m0, s10, 0x2000
	s_add_i32 s10, s44, s7
	global_load_lds_dwordx4 v[208:209], off
	v_lshl_add_u64 v[208:209], v[212:213], 0, s[34:35]
	s_mov_b32 m0, s10
	s_nop 0
	global_load_lds_dwordx4 v[208:209], off
	v_lshl_add_u64 v[208:209], v[214:215], 0, s[34:35]
	s_add_i32 m0, s10, 0x2000
	s_nop 0
	global_load_lds_dwordx4 v[208:209], off
	v_lshl_add_u64 v[208:209], v[216:217], 0, s[34:35]
	s_mov_b32 m0, s16
	s_nop 0
	global_load_lds_dwordx4 v[208:209], off
	v_lshl_add_u64 v[208:209], v[222:223], 0, s[34:35]
	s_mov_b32 m0, s17
	s_nop 0
	global_load_lds_dwordx4 v[208:209], off
	s_waitcnt vmcnt(8)
	s_waitcnt lgkmcnt(0)
	s_setprio 1
	s_barrier
	v_mfma_f32_16x16x32_bf16 v[62:65], v[140:143], v[176:179], v[62:65]
	v_mfma_f32_16x16x32_bf16 v[58:61], v[152:155], v[176:179], v[58:61]
	v_mfma_f32_16x16x32_bf16 v[46:49], v[140:143], v[184:187], v[46:49]
	v_mfma_f32_16x16x32_bf16 v[42:45], v[152:155], v[184:187], v[42:45]
	v_mfma_f32_16x16x32_bf16 v[30:33], v[140:143], v[192:195], v[30:33]
	v_mfma_f32_16x16x32_bf16 v[26:29], v[152:155], v[192:195], v[26:29]
	v_mfma_f32_16x16x32_bf16 v[14:17], v[140:143], v[200:203], v[14:17]
	v_mfma_f32_16x16x32_bf16 v[10:13], v[152:155], v[200:203], v[10:13]
	v_mfma_f32_16x16x32_bf16 v[62:65], v[148:151], v[180:183], v[62:65]
	v_mfma_f32_16x16x32_bf16 v[58:61], v[156:159], v[180:183], v[58:61]
	v_mfma_f32_16x16x32_bf16 v[46:49], v[148:151], v[188:191], v[46:49]
	v_mfma_f32_16x16x32_bf16 v[42:45], v[156:159], v[188:191], v[42:45]
	v_mfma_f32_16x16x32_bf16 v[30:33], v[148:151], v[196:199], v[30:33]
	v_mfma_f32_16x16x32_bf16 v[26:29], v[156:159], v[196:199], v[26:29]
	v_mfma_f32_16x16x32_bf16 v[14:17], v[148:151], v[204:207], v[14:17]
	v_mfma_f32_16x16x32_bf16 v[10:13], v[156:159], v[204:207], v[10:13]
	v_mfma_f32_16x16x32_bf16 v[54:57], v[160:163], v[176:179], v[54:57]
	v_mfma_f32_16x16x32_bf16 v[50:53], v[168:171], v[176:179], v[50:53]
	v_mfma_f32_16x16x32_bf16 v[38:41], v[160:163], v[184:187], v[38:41]
	v_mfma_f32_16x16x32_bf16 v[34:37], v[168:171], v[184:187], v[34:37]
	v_mfma_f32_16x16x32_bf16 v[22:25], v[160:163], v[192:195], v[22:25]
	v_mfma_f32_16x16x32_bf16 v[18:21], v[168:171], v[192:195], v[18:21]
	v_mfma_f32_16x16x32_bf16 v[6:9], v[160:163], v[200:203], v[6:9]
	v_mfma_f32_16x16x32_bf16 v[2:5], v[168:171], v[200:203], v[2:5]
	v_mfma_f32_16x16x32_bf16 v[54:57], v[164:167], v[180:183], v[54:57]
	v_mfma_f32_16x16x32_bf16 v[50:53], v[172:175], v[180:183], v[50:53]
	v_mfma_f32_16x16x32_bf16 v[38:41], v[164:167], v[188:191], v[38:41]
	v_mfma_f32_16x16x32_bf16 v[34:37], v[172:175], v[188:191], v[34:37]
	v_mfma_f32_16x16x32_bf16 v[22:25], v[164:167], v[196:199], v[22:25]
	v_mfma_f32_16x16x32_bf16 v[18:21], v[172:175], v[196:199], v[18:21]
	v_mfma_f32_16x16x32_bf16 v[6:9], v[164:167], v[204:207], v[6:9]
	v_mfma_f32_16x16x32_bf16 v[2:5], v[172:175], v[204:207], v[2:5]
	s_barrier
	s_setprio 0
	s_add_u32 s8, s8, 0x100
	s_addc_u32 s9, s9, 0
	s_add_u32 s12, s12, 0x100
	s_addc_u32 s13, s13, 0
	s_cmp_ge_u32 s14, s56
	s_mov_b32 s10, s14
	s_cbranch_scc0 .LBB0_223
	s_and_b64 vcc, exec, s[46:47]
	s_cbranch_vccz .LBB0_226
	s_barrier

; #define PG8_STAGE(bufoff, gbase, voff) do { _Pragma("unroll") for (int _i = 0; _i < 2; ++_i) \
;         __builtin_amdgcn_global_load_lds((const unsigned*)((const char*)(gbase) + (voff)[_i]), (PG8_LAS unsigned*)(lds + (bufoff) + ldsw + _i * 8192), 16, 0, 0); } while (0)
; #define PG8_LDA(dst, b, h) do { _Pragma("unroll") for (int m = 0; m < 4; ++m) _Pragma("unroll") for (int k = 0; k < 2; ++k) dst[m][k] = *(const PG8_LAS bf16x8*)(lds + PG8_SA(b, h) + aoff + m * 2048 + k * 1024); } while (0)
; #define PG8_LDB(dst, b, h) do { _Pragma("unroll") for (int n = 0; n < 2; ++n) _Pragma("unroll") for (int k = 0; k < 2; ++k) dst[n][k] = *(const PG8_LAS bf16x8*)(lds + PG8_SB(b, h) + boff + n * 2048 + k * 1024); } while (0)
; #define PG8_MMA(ai, bj, At, Bt) do { __builtin_amdgcn_s_setprio(1); _Pragma("unroll") for (int m = 0; m < 4; ++m) _Pragma("unroll") for (int n = 0; n < 2; ++n) _Pragma("unroll") for (int k = 0; k < 2; ++k) \
;         acc[ai][bj][m][n] = __builtin_amdgcn_mfma_f32_16x16x32_bf16(Bt[n][k], At[m][k], acc[ai][bj][m][n], 0, 0, 0); __builtin_amdgcn_s_setprio(0); } while (0)
; #define PG8_WAIT_V(n) asm volatile("s_waitcnt vmcnt(" #n ")" ::: "memory")
; #define PG8_WAIT_L(n) asm volatile("s_waitcnt lgkmcnt(" #n ")" ::: "memory")
; #define PG8_BAR __builtin_amdgcn_s_barrier()
; #define PG8_SCHED __builtin_amdgcn_sched_barrier(0)
; template <class Epi, class Sched, bool ALIGN_EPI = false, bool SP2 = false>
; __device__ __forceinline__ void gemm_phase(PG8_LAS unsigned char* lds, const Gemm g, const Sched& S, const Epi& E) {
;     ...
;             PG8_LDB(B0, 0, 0); PG8_LDB(B1, 0, 1); PG8_SCHED; PG8_LDA(At, 0, 0); PG8_STAGE(PG8_SA(1, 1), a1 + hstep, voffA);
;             PG8_WAIT_V(8); PG8_WAIT_L(0); PG8_BAR; PG8_MMA(0, 0, At, B0); PG8_MMA(0, 1, At, B1); PG8_BAR; PG8_SCHED;
;             PG8_LDA(At, 0, 1); PG8_STAGE(PG8_SB(0, 0), b2, voffB); PG8_STAGE(PG8_SB(0, 1), b2 + hstep, voffB); PG8_STAGE(PG8_SA(0, 0), a2, voffA);
.LBB0_559:
	s_add_u32 s10, s50, 0xfff80080
	s_addc_u32 s11, s51, -1
	s_add_i32 s60, 0, 0x10000
	s_cmp_eq_u32 s59, 28
	s_cselect_b32 s53, s37, s11
	s_cselect_b32 s52, s43, s10
	v_add_u32_e32 v144, s60, v149
	s_cselect_b32 s11, s23, s58
	s_cselect_b32 s10, s56, s57
	s_add_i32 s62, 0, 0x14000
	ds_read_b128 v[140:143], v144
	ds_read_b128 v[152:155], v144 offset:1024
	ds_read_b128 v[156:159], v144 offset:2048
	ds_read_b128 v[160:163], v144 offset:3072
	v_add_u32_e32 v144, s62, v149
	ds_read_b128 v[164:167], v144
	ds_read_b128 v[168:171], v144 offset:1024
	ds_read_b128 v[172:175], v144 offset:2048
	ds_read_b128 v[176:179], v144 offset:3072
	v_lshl_add_u64 v[144:145], s[50:51], 0, v[136:137]
	s_add_i32 m0, s5, 0xc000
	ds_read_b128 v[180:183], v151
	ds_read_b128 v[184:187], v151 offset:1024
	ds_read_b128 v[188:191], v151 offset:2048
	ds_read_b128 v[192:195], v151 offset:3072
	ds_read_b128 v[196:199], v151 offset:4096
	ds_read_b128 v[200:203], v151 offset:5120
	ds_read_b128 v[204:207], v151 offset:6144
	ds_read_b128 v[208:211], v151 offset:7168
	global_load_lds_dwordx4 v[144:145], off
	v_lshl_add_u64 v[144:145], s[50:51], 0, v[138:139]
	s_add_i32 m0, s5, 0xe000
	s_nop 0
	global_load_lds_dwordx4 v[144:145], off
	s_waitcnt vmcnt(8)
	s_waitcnt lgkmcnt(0)
	s_setprio 1
	s_barrier
	v_mfma_f32_16x16x32_bf16 v[126:129], v[140:143], v[180:183], v[126:129]
	v_mfma_f32_16x16x32_bf16 v[122:125], v[156:159], v[180:183], v[122:125]
	v_mfma_f32_16x16x32_bf16 v[110:113], v[140:143], v[188:191], v[110:113]
	v_mfma_f32_16x16x32_bf16 v[106:109], v[156:159], v[188:191], v[106:109]
	v_mfma_f32_16x16x32_bf16 v[94:97], v[140:143], v[196:199], v[94:97]
	v_mfma_f32_16x16x32_bf16 v[90:93], v[156:159], v[196:199], v[90:93]
	v_mfma_f32_16x16x32_bf16 v[78:81], v[140:143], v[204:207], v[78:81]
	v_mfma_f32_16x16x32_bf16 v[74:77], v[156:159], v[204:207], v[74:77]
	v_mfma_f32_16x16x32_bf16 v[126:129], v[152:155], v[184:187], v[126:129]
	v_mfma_f32_16x16x32_bf16 v[122:125], v[160:163], v[184:187], v[122:125]
	v_mfma_f32_16x16x32_bf16 v[110:113], v[152:155], v[192:195], v[110:113]
	v_mfma_f32_16x16x32_bf16 v[106:109], v[160:163], v[192:195], v[106:109]
	v_mfma_f32_16x16x32_bf16 v[94:97], v[152:155], v[200:203], v[94:97]
	v_mfma_f32_16x16x32_bf16 v[90:93], v[160:163], v[200:203], v[90:93]
	v_mfma_f32_16x16x32_bf16 v[78:81], v[152:155], v[208:211], v[78:81]
	v_mfma_f32_16x16x32_bf16 v[74:77], v[160:163], v[208:211], v[74:77]
	v_mfma_f32_16x16x32_bf16 v[118:121], v[164:167], v[180:183], v[118:121]
	v_mfma_f32_16x16x32_bf16 v[114:117], v[172:175], v[180:183], v[114:117]
	v_mfma_f32_16x16x32_bf16 v[102:105], v[164:167], v[188:191], v[102:105]
	v_mfma_f32_16x16x32_bf16 v[98:101], v[172:175], v[188:191], v[98:101]
	v_mfma_f32_16x16x32_bf16 v[86:89], v[164:167], v[196:199], v[86:89]
	v_mfma_f32_16x16x32_bf16 v[82:85], v[172:175], v[196:199], v[82:85]
	v_mfma_f32_16x16x32_bf16 v[70:73], v[164:167], v[204:207], v[70:73]
	v_mfma_f32_16x16x32_bf16 v[66:69], v[172:175], v[204:207], v[66:69]
	v_mfma_f32_16x16x32_bf16 v[118:121], v[168:171], v[184:187], v[118:121]
	v_mfma_f32_16x16x32_bf16 v[114:117], v[176:179], v[184:187], v[114:117]
	v_mfma_f32_16x16x32_bf16 v[102:105], v[168:171], v[192:195], v[102:105]
	v_mfma_f32_16x16x32_bf16 v[98:101], v[176:179], v[192:195], v[98:101]
	v_mfma_f32_16x16x32_bf16 v[86:89], v[168:171], v[200:203], v[86:89]
	v_mfma_f32_16x16x32_bf16 v[82:85], v[176:179], v[200:203], v[82:85]
	v_mfma_f32_16x16x32_bf16 v[70:73], v[168:171], v[208:211], v[70:73]
	v_mfma_f32_16x16x32_bf16 v[66:69], v[176:179], v[208:211], v[66:69]
	s_barrier
	s_setprio 0
	s_add_i32 s60, s60, s4
	v_lshl_add_u64 v[144:145], s[10:11], 0, v[0:1]
	s_mov_b32 m0, s60
	ds_read_b128 v[180:183], v151 offset:16384
	ds_read_b128 v[184:187], v151 offset:17408
	ds_read_b128 v[188:191], v151 offset:18432
	ds_read_b128 v[192:195], v151 offset:19456
	ds_read_b128 v[196:199], v151 offset:20480
	ds_read_b128 v[200:203], v151 offset:21504
	ds_read_b128 v[204:207], v151 offset:22528
	ds_read_b128 v[208:211], v151 offset:23552
	global_load_lds_dwordx4 v[144:145], off
	s_add_i32 m0, s60, 0x2000
	s_add_u32 s60, s10, 0x80000
	v_lshl_add_u64 v[212:213], s[10:11], 0, v[134:135]
	s_addc_u32 s61, s11, 0
	s_add_i32 s62, s62, s4
	global_load_lds_dwordx4 v[212:213], off
	v_lshl_add_u64 v[214:215], s[60:61], 0, v[0:1]
	s_mov_b32 m0, s62
	v_lshl_add_u64 v[216:217], s[52:53], 0, v[132:133]
	global_load_lds_dwordx4 v[214:215], off
	v_lshl_add_u64 v[214:215], s[60:61], 0, v[134:135]
	s_add_i32 m0, s62, 0x2000
	s_nop 0
	global_load_lds_dwordx4 v[214:215], off
	v_lshl_add_u64 v[214:215], s[52:53], 0, v[130:131]
	s_mov_b32 m0, s5
	s_nop 0
	global_load_lds_dwordx4 v[214:215], off
	s_mov_b32 m0, s6
	s_nop 0
	global_load_lds_dwordx4 v[216:217], off
	s_waitcnt vmcnt(8)
	s_waitcnt lgkmcnt(0)
	s_setprio 1
	s_barrier
; #define PG8_STAGE(bufoff, gbase, voff) do { _Pragma("unroll") for (int _i = 0; _i < 2; ++_i) \
;         __builtin_amdgcn_global_load_lds((const unsigned*)((const char*)(gbase) + (voff)[_i]), (PG8_LAS unsigned*)(lds + (bufoff) + ldsw + _i * 8192), 16, 0, 0); } while (0)
; #define PG8_LDA(dst, b, h) do { _Pragma("unroll") for (int m = 0; m < 4; ++m) _Pragma("unroll") for (int k = 0; k < 2; ++k) dst[m][k] = *(const PG8_LAS bf16x8*)(lds + PG8_SA(b, h) + aoff + m * 2048 + k * 1024); } while (0)
; #define PG8_LDB(dst, b, h) do { _Pragma("unroll") for (int n = 0; n < 2; ++n) _Pragma("unroll") for (int k = 0; k < 2; ++k) dst[n][k] = *(const PG8_LAS bf16x8*)(lds + PG8_SB(b, h) + boff + n * 2048 + k * 1024); } while (0)
; #define PG8_MMA(ai, bj, At, Bt) do { __builtin_amdgcn_s_setprio(1); _Pragma("unroll") for (int m = 0; m < 4; ++m) _Pragma("unroll") for (int n = 0; n < 2; ++n) _Pragma("unroll") for (int k = 0; k < 2; ++k) \
;         acc[ai][bj][m][n] = __builtin_amdgcn_mfma_f32_16x16x32_bf16(Bt[n][k], At[m][k], acc[ai][bj][m][n], 0, 0, 0); __builtin_amdgcn_s_setprio(0); } while (0)
; #define PG8_WAIT_V(n) asm volatile("s_waitcnt vmcnt(" #n ")" ::: "memory")
; #define PG8_WAIT_L(n) asm volatile("s_waitcnt lgkmcnt(" #n ")" ::: "memory")
; #define PG8_BAR __builtin_amdgcn_s_barrier()
; #define PG8_SCHED __builtin_amdgcn_sched_barrier(0)
; template <class Epi, class Sched, bool ALIGN_EPI = false, bool SP2 = false>
; __device__ __forceinline__ void gemm_phase(PG8_LAS unsigned char* lds, const Gemm g, const Sched& S, const Epi& E) {
;     ...
;             PG8_WAIT_V(8); PG8_WAIT_L(0); PG8_BAR; PG8_MMA(1, 0, At, B0); PG8_MMA(1, 1, At, B1); PG8_BAR; PG8_SCHED;
;             PG8_LDB(B0, 1, 0); PG8_LDB(B1, 1, 1); PG8_SCHED; PG8_LDA(At, 1, 0); PG8_STAGE(PG8_SA(0, 1), a2 + hstep, voffA);
;             PG8_WAIT_V(8); PG8_WAIT_L(0); PG8_BAR; PG8_MMA(0, 0, At, B0); PG8_MMA(0, 1, At, B1); PG8_BAR; PG8_SCHED;
	v_mfma_f32_16x16x32_bf16 v[62:65], v[140:143], v[180:183], v[62:65]
	v_mfma_f32_16x16x32_bf16 v[58:61], v[156:159], v[180:183], v[58:61]
	v_mfma_f32_16x16x32_bf16 v[46:49], v[140:143], v[188:191], v[46:49]
	v_mfma_f32_16x16x32_bf16 v[42:45], v[156:159], v[188:191], v[42:45]
	v_mfma_f32_16x16x32_bf16 v[30:33], v[140:143], v[196:199], v[30:33]
	v_mfma_f32_16x16x32_bf16 v[26:29], v[156:159], v[196:199], v[26:29]
	v_mfma_f32_16x16x32_bf16 v[14:17], v[140:143], v[204:207], v[14:17]
	v_mfma_f32_16x16x32_bf16 v[10:13], v[156:159], v[204:207], v[10:13]
	v_mfma_f32_16x16x32_bf16 v[62:65], v[152:155], v[184:187], v[62:65]
	v_mfma_f32_16x16x32_bf16 v[58:61], v[160:163], v[184:187], v[58:61]
	v_mfma_f32_16x16x32_bf16 v[46:49], v[152:155], v[192:195], v[46:49]
	v_mfma_f32_16x16x32_bf16 v[42:45], v[160:163], v[192:195], v[42:45]
	v_mfma_f32_16x16x32_bf16 v[30:33], v[152:155], v[200:203], v[30:33]
	v_mfma_f32_16x16x32_bf16 v[26:29], v[160:163], v[200:203], v[26:29]
	v_mfma_f32_16x16x32_bf16 v[14:17], v[152:155], v[208:211], v[14:17]
	v_mfma_f32_16x16x32_bf16 v[10:13], v[160:163], v[208:211], v[10:13]
	v_mfma_f32_16x16x32_bf16 v[54:57], v[164:167], v[180:183], v[54:57]
	v_mfma_f32_16x16x32_bf16 v[50:53], v[172:175], v[180:183], v[50:53]
	v_mfma_f32_16x16x32_bf16 v[38:41], v[164:167], v[188:191], v[38:41]
	v_mfma_f32_16x16x32_bf16 v[34:37], v[172:175], v[188:191], v[34:37]
	v_mfma_f32_16x16x32_bf16 v[22:25], v[164:167], v[196:199], v[22:25]
	v_mfma_f32_16x16x32_bf16 v[18:21], v[172:175], v[196:199], v[18:21]
	v_mfma_f32_16x16x32_bf16 v[6:9], v[164:167], v[204:207], v[6:9]
	v_mfma_f32_16x16x32_bf16 v[2:5], v[172:175], v[204:207], v[2:5]
	v_mfma_f32_16x16x32_bf16 v[54:57], v[168:171], v[184:187], v[54:57]
	v_mfma_f32_16x16x32_bf16 v[50:53], v[176:179], v[184:187], v[50:53]
	v_mfma_f32_16x16x32_bf16 v[38:41], v[168:171], v[192:195], v[38:41]
	v_mfma_f32_16x16x32_bf16 v[34:37], v[176:179], v[192:195], v[34:37]
	v_mfma_f32_16x16x32_bf16 v[22:25], v[168:171], v[200:203], v[22:25]
	v_mfma_f32_16x16x32_bf16 v[18:21], v[176:179], v[200:203], v[18:21]
	v_mfma_f32_16x16x32_bf16 v[6:9], v[168:171], v[208:211], v[6:9]
	v_mfma_f32_16x16x32_bf16 v[2:5], v[176:179], v[208:211], v[2:5]
	s_barrier
	s_setprio 0
	s_add_i32 s60, 0, 0x18000
	v_add_u32_e32 v146, s60, v149
	s_add_i32 s61, 0, 0x1c000
	ds_read_b128 v[140:143], v146
	ds_read_b128 v[152:155], v146 offset:1024
	ds_read_b128 v[156:159], v146 offset:2048
	ds_read_b128 v[160:163], v146 offset:3072
	v_add_u32_e32 v146, s61, v149
	ds_read_b128 v[164:167], v146
	ds_read_b128 v[168:171], v146 offset:1024
	ds_read_b128 v[172:175], v146 offset:2048
	ds_read_b128 v[176:179], v146 offset:3072
	s_add_u32 s52, s52, 0x80000
	s_addc_u32 s53, s53, 0
	s_mov_b32 m0, s7
	v_lshl_add_u64 v[222:223], s[52:53], 0, v[130:131]
	ds_read_b128 v[180:183], v151 offset:32768
	ds_read_b128 v[184:187], v151 offset:33792
	ds_read_b128 v[188:191], v151 offset:34816
	ds_read_b128 v[192:195], v151 offset:35840
	ds_read_b128 v[196:199], v151 offset:36864
	ds_read_b128 v[200:203], v151 offset:37888
	ds_read_b128 v[204:207], v151 offset:38912
	ds_read_b128 v[208:211], v151 offset:39936
	global_load_lds_dwordx4 v[222:223], off
	v_lshl_add_u64 v[222:223], s[52:53], 0, v[132:133]
	s_mov_b32 m0, s17
	s_nop 0
	global_load_lds_dwordx4 v[222:223], off
	s_waitcnt vmcnt(8)
	s_waitcnt lgkmcnt(0)
	s_setprio 1
	s_barrier
	v_mfma_f32_16x16x32_bf16 v[126:129], v[140:143], v[180:183], v[126:129]
	v_mfma_f32_16x16x32_bf16 v[122:125], v[156:159], v[180:183], v[122:125]
	v_mfma_f32_16x16x32_bf16 v[110:113], v[140:143], v[188:191], v[110:113]
	v_mfma_f32_16x16x32_bf16 v[106:109], v[156:159], v[188:191], v[106:109]
	v_mfma_f32_16x16x32_bf16 v[94:97], v[140:143], v[196:199], v[94:97]
	v_mfma_f32_16x16x32_bf16 v[90:93], v[156:159], v[196:199], v[90:93]
	v_mfma_f32_16x16x32_bf16 v[78:81], v[140:143], v[204:207], v[78:81]
	v_mfma_f32_16x16x32_bf16 v[74:77], v[156:159], v[204:207], v[74:77]
	v_mfma_f32_16x16x32_bf16 v[126:129], v[152:155], v[184:187], v[126:129]
	v_mfma_f32_16x16x32_bf16 v[122:125], v[160:163], v[184:187], v[122:125]
	v_mfma_f32_16x16x32_bf16 v[110:113], v[152:155], v[192:195], v[110:113]
	v_mfma_f32_16x16x32_bf16 v[106:109], v[160:163], v[192:195], v[106:109]
	v_mfma_f32_16x16x32_bf16 v[94:97], v[152:155], v[200:203], v[94:97]
	v_mfma_f32_16x16x32_bf16 v[90:93], v[160:163], v[200:203], v[90:93]
	v_mfma_f32_16x16x32_bf16 v[78:81], v[152:155], v[208:211], v[78:81]
	v_mfma_f32_16x16x32_bf16 v[74:77], v[160:163], v[208:211], v[74:77]
	v_mfma_f32_16x16x32_bf16 v[118:121], v[164:167], v[180:183], v[118:121]
	v_mfma_f32_16x16x32_bf16 v[114:117], v[172:175], v[180:183], v[114:117]
	v_mfma_f32_16x16x32_bf16 v[102:105], v[164:167], v[188:191], v[102:105]
	v_mfma_f32_16x16x32_bf16 v[98:101], v[172:175], v[188:191], v[98:101]
	v_mfma_f32_16x16x32_bf16 v[86:89], v[164:167], v[196:199], v[86:89]
	v_mfma_f32_16x16x32_bf16 v[82:85], v[172:175], v[196:199], v[82:85]
	v_mfma_f32_16x16x32_bf16 v[70:73], v[164:167], v[204:207], v[70:73]
	v_mfma_f32_16x16x32_bf16 v[66:69], v[172:175], v[204:207], v[66:69]
	v_mfma_f32_16x16x32_bf16 v[118:121], v[168:171], v[184:187], v[118:121]
	v_mfma_f32_16x16x32_bf16 v[114:117], v[176:179], v[184:187], v[114:117]
	v_mfma_f32_16x16x32_bf16 v[102:105], v[168:171], v[192:195], v[102:105]
	v_mfma_f32_16x16x32_bf16 v[98:101], v[176:179], v[192:195], v[98:101]
	v_mfma_f32_16x16x32_bf16 v[86:89], v[168:171], v[200:203], v[86:89]
	v_mfma_f32_16x16x32_bf16 v[82:85], v[176:179], v[200:203], v[82:85]
	v_mfma_f32_16x16x32_bf16 v[70:73], v[168:171], v[208:211], v[70:73]
	v_mfma_f32_16x16x32_bf16 v[66:69], v[176:179], v[208:211], v[66:69]
	s_barrier
; #define PG8_STAGE(bufoff, gbase, voff) do { _Pragma("unroll") for (int _i = 0; _i < 2; ++_i) \
;         __builtin_amdgcn_global_load_lds((const unsigned*)((const char*)(gbase) + (voff)[_i]), (PG8_LAS unsigned*)(lds + (bufoff) + ldsw + _i * 8192), 16, 0, 0); } while (0)
; #define PG8_LDA(dst, b, h) do { _Pragma("unroll") for (int m = 0; m < 4; ++m) _Pragma("unroll") for (int k = 0; k < 2; ++k) dst[m][k] = *(const PG8_LAS bf16x8*)(lds + PG8_SA(b, h) + aoff + m * 2048 + k * 1024); } while (0)
; #define PG8_MMA(ai, bj, At, Bt) do { __builtin_amdgcn_s_setprio(1); _Pragma("unroll") for (int m = 0; m < 4; ++m) _Pragma("unroll") for (int n = 0; n < 2; ++n) _Pragma("unroll") for (int k = 0; k < 2; ++k) \
;         acc[ai][bj][m][n] = __builtin_amdgcn_mfma_f32_16x16x32_bf16(Bt[n][k], At[m][k], acc[ai][bj][m][n], 0, 0, 0); __builtin_amdgcn_s_setprio(0); } while (0)
; #define PG8_WAIT_V(n) asm volatile("s_waitcnt vmcnt(" #n ")" ::: "memory")
; #define PG8_WAIT_L(n) asm volatile("s_waitcnt lgkmcnt(" #n ")" ::: "memory")
; #define PG8_BAR __builtin_amdgcn_s_barrier()
; #define PG8_SCHED __builtin_amdgcn_sched_barrier(0)
; template <class Epi, class Sched, bool ALIGN_EPI = false, bool SP2 = false>
; __device__ __forceinline__ void gemm_phase(PG8_LAS unsigned char* lds, const Gemm g, const Sched& S, const Epi& E) {
;     ...
;         for (int t = 0; t < nt; t += 2) {
;             const bool last = (t == nt - 2);
;             const char* a1 = cA + (size_t)(t + 1) * kstep;
;             const char* a2 = last ? nA : cA + (size_t)(t + 2) * kstep; const char* b2 = last ? nB : cB + (size_t)(t + 2) * kstep;
;             const char* a3 = a2 + kstep; const char* b3 = b2 + kstep;
;     ...
;             PG8_LDA(At, 1, 1); PG8_STAGE(PG8_SB(1, 0), b3, voffB); PG8_STAGE(PG8_SB(1, 1), b3 + hstep, voffB); PG8_STAGE(PG8_SA(1, 0), a3, voffA);
;             PG8_WAIT_V(8); PG8_WAIT_L(0); PG8_BAR; PG8_MMA(1, 0, At, B0); PG8_MMA(1, 1, At, B1); PG8_BAR; PG8_SCHED;
	s_setprio 0
	s_add_i32 s52, s60, s4
	v_lshl_add_u64 v[144:145], v[144:145], 0, s[34:35]
	s_mov_b32 m0, s52
	ds_read_b128 v[180:183], v151 offset:49152
	ds_read_b128 v[184:187], v151 offset:50176
	ds_read_b128 v[188:191], v151 offset:51200
	ds_read_b128 v[192:195], v151 offset:52224
	ds_read_b128 v[196:199], v151 offset:53248
	ds_read_b128 v[200:203], v151 offset:54272
	ds_read_b128 v[204:207], v151 offset:55296
	ds_read_b128 v[208:211], v151 offset:56320
	global_load_lds_dwordx4 v[144:145], off
	s_add_i32 m0, s52, 0x2000
	s_add_u32 s10, s10, 0x80080
	v_lshl_add_u64 v[144:145], v[212:213], 0, s[34:35]
	s_addc_u32 s11, s11, 0
	s_add_i32 s52, s61, s4
	global_load_lds_dwordx4 v[144:145], off
	v_lshl_add_u64 v[144:145], s[10:11], 0, v[0:1]
	s_mov_b32 m0, s52
	s_nop 0
	global_load_lds_dwordx4 v[144:145], off
	v_lshl_add_u64 v[144:145], s[10:11], 0, v[134:135]
	s_add_i32 m0, s52, 0x2000
	s_nop 0
	global_load_lds_dwordx4 v[144:145], off
	v_lshl_add_u64 v[144:145], v[214:215], 0, s[34:35]
	s_mov_b32 m0, s30
	s_nop 0
	global_load_lds_dwordx4 v[144:145], off
	v_lshl_add_u64 v[144:145], v[216:217], 0, s[34:35]
	s_mov_b32 m0, s47
	s_nop 0
	global_load_lds_dwordx4 v[144:145], off
	s_waitcnt vmcnt(8)
	s_waitcnt lgkmcnt(0)
	s_setprio 1
	s_barrier
	v_mfma_f32_16x16x32_bf16 v[62:65], v[140:143], v[180:183], v[62:65]
	v_mfma_f32_16x16x32_bf16 v[58:61], v[156:159], v[180:183], v[58:61]
	v_mfma_f32_16x16x32_bf16 v[46:49], v[140:143], v[188:191], v[46:49]
	v_mfma_f32_16x16x32_bf16 v[42:45], v[156:159], v[188:191], v[42:45]
	v_mfma_f32_16x16x32_bf16 v[30:33], v[140:143], v[196:199], v[30:33]
	v_mfma_f32_16x16x32_bf16 v[26:29], v[156:159], v[196:199], v[26:29]
	v_mfma_f32_16x16x32_bf16 v[14:17], v[140:143], v[204:207], v[14:17]
	v_mfma_f32_16x16x32_bf16 v[10:13], v[156:159], v[204:207], v[10:13]
	v_mfma_f32_16x16x32_bf16 v[62:65], v[152:155], v[184:187], v[62:65]
	v_mfma_f32_16x16x32_bf16 v[58:61], v[160:163], v[184:187], v[58:61]
	v_mfma_f32_16x16x32_bf16 v[46:49], v[152:155], v[192:195], v[46:49]
	v_mfma_f32_16x16x32_bf16 v[42:45], v[160:163], v[192:195], v[42:45]
	v_mfma_f32_16x16x32_bf16 v[30:33], v[152:155], v[200:203], v[30:33]
	v_mfma_f32_16x16x32_bf16 v[26:29], v[160:163], v[200:203], v[26:29]
	v_mfma_f32_16x16x32_bf16 v[14:17], v[152:155], v[208:211], v[14:17]
	v_mfma_f32_16x16x32_bf16 v[10:13], v[160:163], v[208:211], v[10:13]
	v_mfma_f32_16x16x32_bf16 v[54:57], v[164:167], v[180:183], v[54:57]
	v_mfma_f32_16x16x32_bf16 v[50:53], v[172:175], v[180:183], v[50:53]
	v_mfma_f32_16x16x32_bf16 v[38:41], v[164:167], v[188:191], v[38:41]
	v_mfma_f32_16x16x32_bf16 v[34:37], v[172:175], v[188:191], v[34:37]
	v_mfma_f32_16x16x32_bf16 v[22:25], v[164:167], v[196:199], v[22:25]
	v_mfma_f32_16x16x32_bf16 v[18:21], v[172:175], v[196:199], v[18:21]
	v_mfma_f32_16x16x32_bf16 v[6:9], v[164:167], v[204:207], v[6:9]
	v_mfma_f32_16x16x32_bf16 v[2:5], v[172:175], v[204:207], v[2:5]
	v_mfma_f32_16x16x32_bf16 v[54:57], v[168:171], v[184:187], v[54:57]
	v_mfma_f32_16x16x32_bf16 v[50:53], v[176:179], v[184:187], v[50:53]
	v_mfma_f32_16x16x32_bf16 v[38:41], v[168:171], v[192:195], v[38:41]
	v_mfma_f32_16x16x32_bf16 v[34:37], v[176:179], v[192:195], v[34:37]
	v_mfma_f32_16x16x32_bf16 v[22:25], v[168:171], v[200:203], v[22:25]
	v_mfma_f32_16x16x32_bf16 v[18:21], v[176:179], v[200:203], v[18:21]
	v_mfma_f32_16x16x32_bf16 v[6:9], v[168:171], v[208:211], v[6:9]
	v_mfma_f32_16x16x32_bf16 v[2:5], v[176:179], v[208:211], v[2:5]
	s_barrier
	s_setprio 0
	s_add_i32 s59, s59, 2
	s_add_u32 s50, s50, 0x100
	s_addc_u32 s51, s51, 0
	s_add_u32 s57, s57, 0x100
	s_addc_u32 s58, s58, 0
	s_cmp_gt_u32 s59, 29
	s_cbranch_scc0 .LBB0_559
	s_and_b64 vcc, exec, s[14:15]
	s_cbranch_vccz .LBB0_562
	s_barrier

; #define PG8_STAGE(bufoff, gbase, voff) do { _Pragma("unroll") for (int _i = 0; _i < 2; ++_i) \
;         __builtin_amdgcn_global_load_lds((const unsigned*)((const char*)(gbase) + (voff)[_i]), (PG8_LAS unsigned*)(lds + (bufoff) + ldsw + _i * 8192), 16, 0, 0); } while (0)
; #define PG8_LDA(dst, b, h) do { _Pragma("unroll") for (int m = 0; m < 4; ++m) _Pragma("unroll") for (int k = 0; k < 2; ++k) dst[m][k] = *(const PG8_LAS bf16x8*)(lds + PG8_SA(b, h) + aoff + m * 2048 + k * 1024); } while (0)
; #define PG8_LDB(dst, b, h) do { _Pragma("unroll") for (int n = 0; n < 2; ++n) _Pragma("unroll") for (int k = 0; k < 2; ++k) dst[n][k] = *(const PG8_LAS bf16x8*)(lds + PG8_SB(b, h) + boff + n * 2048 + k * 1024); } while (0)
; #define PG8_MMA(ai, bj, At, Bt) do { __builtin_amdgcn_s_setprio(1); _Pragma("unroll") for (int m = 0; m < 4; ++m) _Pragma("unroll") for (int n = 0; n < 2; ++n) _Pragma("unroll") for (int k = 0; k < 2; ++k) \
;         acc[ai][bj][m][n] = __builtin_amdgcn_mfma_f32_16x16x32_bf16(Bt[n][k], At[m][k], acc[ai][bj][m][n], 0, 0, 0); __builtin_amdgcn_s_setprio(0); } while (0)
; #define PG8_WAIT_V(n) asm volatile("s_waitcnt vmcnt(" #n ")" ::: "memory")
; #define PG8_WAIT_L(n) asm volatile("s_waitcnt lgkmcnt(" #n ")" ::: "memory")
; #define PG8_BAR __builtin_amdgcn_s_barrier()
; #define PG8_SCHED __builtin_amdgcn_sched_barrier(0)
; template <class Epi, class Sched, bool ALIGN_EPI = false, bool SP2 = false>
; __device__ __forceinline__ void gemm_phase(PG8_LAS unsigned char* lds, const Gemm g, const Sched& S, const Epi& E) {
;     ...
;             PG8_LDB(B0, 0, 0); PG8_LDB(B1, 0, 1); PG8_SCHED; PG8_LDA(At, 0, 0); PG8_STAGE(PG8_SA(1, 1), a1 + hstep, voffA);
;             PG8_WAIT_V(8); PG8_WAIT_L(0); PG8_BAR; PG8_MMA(0, 0, At, B0); PG8_MMA(0, 1, At, B1); PG8_BAR; PG8_SCHED;
;             PG8_LDA(At, 0, 1); PG8_STAGE(PG8_SB(0, 0), b2, voffB); PG8_STAGE(PG8_SB(0, 1), b2 + hstep, voffB); PG8_STAGE(PG8_SA(0, 0), a2, voffA);
.LBB0_599:
	s_add_u32 s10, s36, 0xfff80080
	s_addc_u32 s11, s37, -1
	s_add_i32 s55, 0, 0x10000
	s_cmp_eq_u32 s54, 28
	s_cselect_b32 s41, s19, s11
	s_cselect_b32 s40, s50, s10
	v_add_u32_e32 v140, s55, v143
	s_cselect_b32 s11, s17, s53
	s_cselect_b32 s10, s51, s52
	s_add_i32 s58, 0, 0x14000
	ds_read_b128 v[146:149], v140
	ds_read_b128 v[150:153], v140 offset:1024
	ds_read_b128 v[154:157], v140 offset:2048
	ds_read_b128 v[158:161], v140 offset:3072
	v_add_u32_e32 v140, s58, v143
	ds_read_b128 v[162:165], v140
	ds_read_b128 v[166:169], v140 offset:1024
	ds_read_b128 v[170:173], v140 offset:2048
	ds_read_b128 v[174:177], v140 offset:3072
	v_lshl_add_u64 v[140:141], s[36:37], 0, v[136:137]
	s_add_i32 m0, s7, 0xc000
	ds_read_b128 v[178:181], v145
	ds_read_b128 v[182:185], v145 offset:1024
	ds_read_b128 v[186:189], v145 offset:2048
	ds_read_b128 v[190:193], v145 offset:3072
	ds_read_b128 v[194:197], v145 offset:4096
	ds_read_b128 v[198:201], v145 offset:5120
	ds_read_b128 v[202:205], v145 offset:6144
	ds_read_b128 v[206:209], v145 offset:7168
	global_load_lds_dwordx4 v[140:141], off
	v_lshl_add_u64 v[140:141], s[36:37], 0, v[138:139]
	s_add_i32 m0, s7, 0xe000
	s_nop 0
	global_load_lds_dwordx4 v[140:141], off
	s_waitcnt vmcnt(8)
	s_waitcnt lgkmcnt(0)
	s_setprio 1
	s_barrier
	v_mfma_f32_16x16x32_bf16 v[126:129], v[146:149], v[178:181], v[126:129]
	v_mfma_f32_16x16x32_bf16 v[122:125], v[154:157], v[178:181], v[122:125]
	v_mfma_f32_16x16x32_bf16 v[118:121], v[146:149], v[186:189], v[118:121]
	v_mfma_f32_16x16x32_bf16 v[110:113], v[154:157], v[186:189], v[110:113]
	v_mfma_f32_16x16x32_bf16 v[102:105], v[146:149], v[194:197], v[102:105]
	v_mfma_f32_16x16x32_bf16 v[94:97], v[154:157], v[194:197], v[94:97]
	v_mfma_f32_16x16x32_bf16 v[86:89], v[146:149], v[202:205], v[86:89]
	v_mfma_f32_16x16x32_bf16 v[78:81], v[154:157], v[202:205], v[78:81]
	v_mfma_f32_16x16x32_bf16 v[126:129], v[150:153], v[182:185], v[126:129]
	v_mfma_f32_16x16x32_bf16 v[122:125], v[158:161], v[182:185], v[122:125]
	v_mfma_f32_16x16x32_bf16 v[118:121], v[150:153], v[190:193], v[118:121]
	v_mfma_f32_16x16x32_bf16 v[110:113], v[158:161], v[190:193], v[110:113]
	v_mfma_f32_16x16x32_bf16 v[102:105], v[150:153], v[198:201], v[102:105]
	v_mfma_f32_16x16x32_bf16 v[94:97], v[158:161], v[198:201], v[94:97]
	v_mfma_f32_16x16x32_bf16 v[86:89], v[150:153], v[206:209], v[86:89]
	v_mfma_f32_16x16x32_bf16 v[78:81], v[158:161], v[206:209], v[78:81]
	v_mfma_f32_16x16x32_bf16 v[114:117], v[162:165], v[178:181], v[114:117]
	v_mfma_f32_16x16x32_bf16 v[106:109], v[170:173], v[178:181], v[106:109]
	v_mfma_f32_16x16x32_bf16 v[98:101], v[162:165], v[186:189], v[98:101]
	v_mfma_f32_16x16x32_bf16 v[90:93], v[170:173], v[186:189], v[90:93]
	v_mfma_f32_16x16x32_bf16 v[82:85], v[162:165], v[194:197], v[82:85]
	v_mfma_f32_16x16x32_bf16 v[74:77], v[170:173], v[194:197], v[74:77]
	v_mfma_f32_16x16x32_bf16 v[70:73], v[162:165], v[202:205], v[70:73]
	v_mfma_f32_16x16x32_bf16 v[66:69], v[170:173], v[202:205], v[66:69]
	v_mfma_f32_16x16x32_bf16 v[114:117], v[166:169], v[182:185], v[114:117]
	v_mfma_f32_16x16x32_bf16 v[106:109], v[174:177], v[182:185], v[106:109]
	v_mfma_f32_16x16x32_bf16 v[98:101], v[166:169], v[190:193], v[98:101]
	v_mfma_f32_16x16x32_bf16 v[90:93], v[174:177], v[190:193], v[90:93]
	v_mfma_f32_16x16x32_bf16 v[82:85], v[166:169], v[198:201], v[82:85]
	v_mfma_f32_16x16x32_bf16 v[74:77], v[174:177], v[198:201], v[74:77]
	v_mfma_f32_16x16x32_bf16 v[70:73], v[166:169], v[206:209], v[70:73]
	v_mfma_f32_16x16x32_bf16 v[66:69], v[174:177], v[206:209], v[66:69]
	s_barrier
	s_setprio 0
	s_add_i32 s55, s55, s4
	v_lshl_add_u64 v[140:141], s[10:11], 0, v[0:1]
	s_mov_b32 m0, s55
	ds_read_b128 v[178:181], v145 offset:16384
	ds_read_b128 v[182:185], v145 offset:17408
	ds_read_b128 v[186:189], v145 offset:18432
	ds_read_b128 v[190:193], v145 offset:19456
	ds_read_b128 v[194:197], v145 offset:20480
	ds_read_b128 v[198:201], v145 offset:21504
	ds_read_b128 v[202:205], v145 offset:22528
	ds_read_b128 v[206:209], v145 offset:23552
	global_load_lds_dwordx4 v[140:141], off
	s_add_i32 m0, s55, 0x2000
	s_add_u32 s56, s10, 0x80000
	v_lshl_add_u64 v[210:211], s[10:11], 0, v[134:135]
	s_addc_u32 s57, s11, 0
	s_add_i32 s55, s58, s4
	global_load_lds_dwordx4 v[210:211], off
	v_lshl_add_u64 v[212:213], s[56:57], 0, v[0:1]
	s_mov_b32 m0, s55
	v_lshl_add_u64 v[214:215], s[40:41], 0, v[132:133]
	global_load_lds_dwordx4 v[212:213], off
	v_lshl_add_u64 v[212:213], s[56:57], 0, v[134:135]
	s_add_i32 m0, s55, 0x2000
	s_nop 0
	global_load_lds_dwordx4 v[212:213], off
	v_lshl_add_u64 v[212:213], s[40:41], 0, v[130:131]
	s_mov_b32 m0, s7
	s_nop 0
	global_load_lds_dwordx4 v[212:213], off
	s_mov_b32 m0, s21
	s_nop 0
	global_load_lds_dwordx4 v[214:215], off
	s_waitcnt vmcnt(8)
	s_waitcnt lgkmcnt(0)
	s_setprio 1
	s_barrier
; #define PG8_STAGE(bufoff, gbase, voff) do { _Pragma("unroll") for (int _i = 0; _i < 2; ++_i) \
;         __builtin_amdgcn_global_load_lds((const unsigned*)((const char*)(gbase) + (voff)[_i]), (PG8_LAS unsigned*)(lds + (bufoff) + ldsw + _i * 8192), 16, 0, 0); } while (0)
; #define PG8_LDA(dst, b, h) do { _Pragma("unroll") for (int m = 0; m < 4; ++m) _Pragma("unroll") for (int k = 0; k < 2; ++k) dst[m][k] = *(const PG8_LAS bf16x8*)(lds + PG8_SA(b, h) + aoff + m * 2048 + k * 1024); } while (0)
; #define PG8_LDB(dst, b, h) do { _Pragma("unroll") for (int n = 0; n < 2; ++n) _Pragma("unroll") for (int k = 0; k < 2; ++k) dst[n][k] = *(const PG8_LAS bf16x8*)(lds + PG8_SB(b, h) + boff + n * 2048 + k * 1024); } while (0)
; #define PG8_MMA(ai, bj, At, Bt) do { __builtin_amdgcn_s_setprio(1); _Pragma("unroll") for (int m = 0; m < 4; ++m) _Pragma("unroll") for (int n = 0; n < 2; ++n) _Pragma("unroll") for (int k = 0; k < 2; ++k) \
;         acc[ai][bj][m][n] = __builtin_amdgcn_mfma_f32_16x16x32_bf16(Bt[n][k], At[m][k], acc[ai][bj][m][n], 0, 0, 0); __builtin_amdgcn_s_setprio(0); } while (0)
; #define PG8_WAIT_V(n) asm volatile("s_waitcnt vmcnt(" #n ")" ::: "memory")
; #define PG8_WAIT_L(n) asm volatile("s_waitcnt lgkmcnt(" #n ")" ::: "memory")
; #define PG8_BAR __builtin_amdgcn_s_barrier()
; #define PG8_SCHED __builtin_amdgcn_sched_barrier(0)
; template <class Epi, class Sched, bool ALIGN_EPI = false, bool SP2 = false>
; __device__ __forceinline__ void gemm_phase(PG8_LAS unsigned char* lds, const Gemm g, const Sched& S, const Epi& E) {
;     ...
;             PG8_WAIT_V(8); PG8_WAIT_L(0); PG8_BAR; PG8_MMA(1, 0, At, B0); PG8_MMA(1, 1, At, B1); PG8_BAR; PG8_SCHED;
;             PG8_LDB(B0, 1, 0); PG8_LDB(B1, 1, 1); PG8_SCHED; PG8_LDA(At, 1, 0); PG8_STAGE(PG8_SA(0, 1), a2 + hstep, voffA);
;             PG8_WAIT_V(8); PG8_WAIT_L(0); PG8_BAR; PG8_MMA(0, 0, At, B0); PG8_MMA(0, 1, At, B1); PG8_BAR; PG8_SCHED;
	v_mfma_f32_16x16x32_bf16 v[62:65], v[146:149], v[178:181], v[62:65]
	v_mfma_f32_16x16x32_bf16 v[58:61], v[154:157], v[178:181], v[58:61]
	v_mfma_f32_16x16x32_bf16 v[54:57], v[146:149], v[186:189], v[54:57]
	v_mfma_f32_16x16x32_bf16 v[46:49], v[154:157], v[186:189], v[46:49]
	v_mfma_f32_16x16x32_bf16 v[38:41], v[146:149], v[194:197], v[38:41]
	v_mfma_f32_16x16x32_bf16 v[30:33], v[154:157], v[194:197], v[30:33]
	v_mfma_f32_16x16x32_bf16 v[22:25], v[146:149], v[202:205], v[22:25]
	v_mfma_f32_16x16x32_bf16 v[14:17], v[154:157], v[202:205], v[14:17]
	v_mfma_f32_16x16x32_bf16 v[62:65], v[150:153], v[182:185], v[62:65]
	v_mfma_f32_16x16x32_bf16 v[58:61], v[158:161], v[182:185], v[58:61]
	v_mfma_f32_16x16x32_bf16 v[54:57], v[150:153], v[190:193], v[54:57]
	v_mfma_f32_16x16x32_bf16 v[46:49], v[158:161], v[190:193], v[46:49]
	v_mfma_f32_16x16x32_bf16 v[38:41], v[150:153], v[198:201], v[38:41]
	v_mfma_f32_16x16x32_bf16 v[30:33], v[158:161], v[198:201], v[30:33]
	v_mfma_f32_16x16x32_bf16 v[22:25], v[150:153], v[206:209], v[22:25]
	v_mfma_f32_16x16x32_bf16 v[14:17], v[158:161], v[206:209], v[14:17]
	v_mfma_f32_16x16x32_bf16 v[50:53], v[162:165], v[178:181], v[50:53]
	v_mfma_f32_16x16x32_bf16 v[42:45], v[170:173], v[178:181], v[42:45]
	v_mfma_f32_16x16x32_bf16 v[34:37], v[162:165], v[186:189], v[34:37]
	v_mfma_f32_16x16x32_bf16 v[26:29], v[170:173], v[186:189], v[26:29]
	v_mfma_f32_16x16x32_bf16 v[18:21], v[162:165], v[194:197], v[18:21]
	v_mfma_f32_16x16x32_bf16 v[10:13], v[170:173], v[194:197], v[10:13]
	v_mfma_f32_16x16x32_bf16 v[6:9], v[162:165], v[202:205], v[6:9]
	v_mfma_f32_16x16x32_bf16 v[2:5], v[170:173], v[202:205], v[2:5]
	v_mfma_f32_16x16x32_bf16 v[50:53], v[166:169], v[182:185], v[50:53]
	v_mfma_f32_16x16x32_bf16 v[42:45], v[174:177], v[182:185], v[42:45]
	v_mfma_f32_16x16x32_bf16 v[34:37], v[166:169], v[190:193], v[34:37]
	v_mfma_f32_16x16x32_bf16 v[26:29], v[174:177], v[190:193], v[26:29]
	v_mfma_f32_16x16x32_bf16 v[18:21], v[166:169], v[198:201], v[18:21]
	v_mfma_f32_16x16x32_bf16 v[10:13], v[174:177], v[198:201], v[10:13]
	v_mfma_f32_16x16x32_bf16 v[6:9], v[166:169], v[206:209], v[6:9]
	v_mfma_f32_16x16x32_bf16 v[2:5], v[174:177], v[206:209], v[2:5]
	s_barrier
	s_setprio 0
	s_add_i32 s55, 0, 0x18000
	s_add_i32 s56, 0, 0x1c000
	v_add_u32_e32 v158, s55, v143
	v_add_u32_e32 v174, s56, v143
	ds_read_b128 v[146:149], v158
	ds_read_b128 v[150:153], v158 offset:1024
	ds_read_b128 v[154:157], v158 offset:2048
	ds_read_b128 v[158:161], v158 offset:3072
	ds_read_b128 v[162:165], v174
	ds_read_b128 v[166:169], v174 offset:1024
	ds_read_b128 v[170:173], v174 offset:2048
	ds_read_b128 v[174:177], v174 offset:3072
	s_add_u32 s40, s40, 0x80000
	s_addc_u32 s41, s41, 0
	s_mov_b32 m0, s30
	v_lshl_add_u64 v[216:217], s[40:41], 0, v[130:131]
	ds_read_b128 v[178:181], v145 offset:32768
	ds_read_b128 v[182:185], v145 offset:33792
	ds_read_b128 v[186:189], v145 offset:34816
	ds_read_b128 v[190:193], v145 offset:35840
	ds_read_b128 v[194:197], v145 offset:36864
	ds_read_b128 v[198:201], v145 offset:37888
	ds_read_b128 v[202:205], v145 offset:38912
	ds_read_b128 v[206:209], v145 offset:39936
	global_load_lds_dwordx4 v[216:217], off
	v_lshl_add_u64 v[216:217], s[40:41], 0, v[132:133]
	s_mov_b32 m0, s42
	s_nop 0
	global_load_lds_dwordx4 v[216:217], off
	s_waitcnt vmcnt(8)
	s_waitcnt lgkmcnt(0)
	s_setprio 1
	s_barrier
	v_mfma_f32_16x16x32_bf16 v[126:129], v[146:149], v[178:181], v[126:129]
	v_mfma_f32_16x16x32_bf16 v[122:125], v[154:157], v[178:181], v[122:125]
	v_mfma_f32_16x16x32_bf16 v[118:121], v[146:149], v[186:189], v[118:121]
	v_mfma_f32_16x16x32_bf16 v[110:113], v[154:157], v[186:189], v[110:113]
	v_mfma_f32_16x16x32_bf16 v[102:105], v[146:149], v[194:197], v[102:105]
	v_mfma_f32_16x16x32_bf16 v[94:97], v[154:157], v[194:197], v[94:97]
	v_mfma_f32_16x16x32_bf16 v[86:89], v[146:149], v[202:205], v[86:89]
	v_mfma_f32_16x16x32_bf16 v[78:81], v[154:157], v[202:205], v[78:81]
	v_mfma_f32_16x16x32_bf16 v[126:129], v[150:153], v[182:185], v[126:129]
	v_mfma_f32_16x16x32_bf16 v[122:125], v[158:161], v[182:185], v[122:125]
	v_mfma_f32_16x16x32_bf16 v[118:121], v[150:153], v[190:193], v[118:121]
	v_mfma_f32_16x16x32_bf16 v[110:113], v[158:161], v[190:193], v[110:113]
	v_mfma_f32_16x16x32_bf16 v[102:105], v[150:153], v[198:201], v[102:105]
	v_mfma_f32_16x16x32_bf16 v[94:97], v[158:161], v[198:201], v[94:97]
	v_mfma_f32_16x16x32_bf16 v[86:89], v[150:153], v[206:209], v[86:89]
	v_mfma_f32_16x16x32_bf16 v[78:81], v[158:161], v[206:209], v[78:81]
	v_mfma_f32_16x16x32_bf16 v[114:117], v[162:165], v[178:181], v[114:117]
	v_mfma_f32_16x16x32_bf16 v[106:109], v[170:173], v[178:181], v[106:109]
	v_mfma_f32_16x16x32_bf16 v[98:101], v[162:165], v[186:189], v[98:101]
	v_mfma_f32_16x16x32_bf16 v[90:93], v[170:173], v[186:189], v[90:93]
	v_mfma_f32_16x16x32_bf16 v[82:85], v[162:165], v[194:197], v[82:85]
	v_mfma_f32_16x16x32_bf16 v[74:77], v[170:173], v[194:197], v[74:77]
	v_mfma_f32_16x16x32_bf16 v[70:73], v[162:165], v[202:205], v[70:73]
	v_mfma_f32_16x16x32_bf16 v[66:69], v[170:173], v[202:205], v[66:69]
	v_mfma_f32_16x16x32_bf16 v[114:117], v[166:169], v[182:185], v[114:117]
	v_mfma_f32_16x16x32_bf16 v[106:109], v[174:177], v[182:185], v[106:109]
	v_mfma_f32_16x16x32_bf16 v[98:101], v[166:169], v[190:193], v[98:101]
	v_mfma_f32_16x16x32_bf16 v[90:93], v[174:177], v[190:193], v[90:93]
	v_mfma_f32_16x16x32_bf16 v[82:85], v[166:169], v[198:201], v[82:85]
	v_mfma_f32_16x16x32_bf16 v[74:77], v[174:177], v[198:201], v[74:77]
	v_mfma_f32_16x16x32_bf16 v[70:73], v[166:169], v[206:209], v[70:73]
	v_mfma_f32_16x16x32_bf16 v[66:69], v[174:177], v[206:209], v[66:69]
	s_barrier
; #define PG8_STAGE(bufoff, gbase, voff) do { _Pragma("unroll") for (int _i = 0; _i < 2; ++_i) \
;         __builtin_amdgcn_global_load_lds((const unsigned*)((const char*)(gbase) + (voff)[_i]), (PG8_LAS unsigned*)(lds + (bufoff) + ldsw + _i * 8192), 16, 0, 0); } while (0)
; #define PG8_LDA(dst, b, h) do { _Pragma("unroll") for (int m = 0; m < 4; ++m) _Pragma("unroll") for (int k = 0; k < 2; ++k) dst[m][k] = *(const PG8_LAS bf16x8*)(lds + PG8_SA(b, h) + aoff + m * 2048 + k * 1024); } while (0)
; #define PG8_MMA(ai, bj, At, Bt) do { __builtin_amdgcn_s_setprio(1); _Pragma("unroll") for (int m = 0; m < 4; ++m) _Pragma("unroll") for (int n = 0; n < 2; ++n) _Pragma("unroll") for (int k = 0; k < 2; ++k) \
;         acc[ai][bj][m][n] = __builtin_amdgcn_mfma_f32_16x16x32_bf16(Bt[n][k], At[m][k], acc[ai][bj][m][n], 0, 0, 0); __builtin_amdgcn_s_setprio(0); } while (0)
; #define PG8_WAIT_V(n) asm volatile("s_waitcnt vmcnt(" #n ")" ::: "memory")
; #define PG8_WAIT_L(n) asm volatile("s_waitcnt lgkmcnt(" #n ")" ::: "memory")
; #define PG8_BAR __builtin_amdgcn_s_barrier()
; #define PG8_SCHED __builtin_amdgcn_sched_barrier(0)
; template <class Epi, class Sched, bool ALIGN_EPI = false, bool SP2 = false>
; __device__ __forceinline__ void gemm_phase(PG8_LAS unsigned char* lds, const Gemm g, const Sched& S, const Epi& E) {
;     ...
;         for (int t = 0; t < nt; t += 2) {
;             const bool last = (t == nt - 2);
;             const char* a1 = cA + (size_t)(t + 1) * kstep;
;             const char* a2 = last ? nA : cA + (size_t)(t + 2) * kstep; const char* b2 = last ? nB : cB + (size_t)(t + 2) * kstep;
;             const char* a3 = a2 + kstep; const char* b3 = b2 + kstep;
;     ...
;             PG8_LDA(At, 1, 1); PG8_STAGE(PG8_SB(1, 0), b3, voffB); PG8_STAGE(PG8_SB(1, 1), b3 + hstep, voffB); PG8_STAGE(PG8_SA(1, 0), a3, voffA);
;             PG8_WAIT_V(8); PG8_WAIT_L(0); PG8_BAR; PG8_MMA(1, 0, At, B0); PG8_MMA(1, 1, At, B1); PG8_BAR; PG8_SCHED;
	s_setprio 0
	s_add_i32 s40, s55, s4
	v_lshl_add_u64 v[140:141], v[140:141], 0, s[34:35]
	s_mov_b32 m0, s40
	ds_read_b128 v[178:181], v145 offset:49152
	ds_read_b128 v[182:185], v145 offset:50176
	ds_read_b128 v[186:189], v145 offset:51200
	ds_read_b128 v[190:193], v145 offset:52224
	ds_read_b128 v[194:197], v145 offset:53248
	ds_read_b128 v[198:201], v145 offset:54272
	ds_read_b128 v[202:205], v145 offset:55296
	ds_read_b128 v[206:209], v145 offset:56320
	global_load_lds_dwordx4 v[140:141], off
	s_add_i32 m0, s40, 0x2000
	s_add_u32 s10, s10, 0x80080
	v_lshl_add_u64 v[140:141], v[210:211], 0, s[34:35]
	s_addc_u32 s11, s11, 0
	s_add_i32 s40, s56, s4
	global_load_lds_dwordx4 v[140:141], off
	v_lshl_add_u64 v[140:141], s[10:11], 0, v[0:1]
	s_mov_b32 m0, s40
	s_nop 0
	global_load_lds_dwordx4 v[140:141], off
	v_lshl_add_u64 v[140:141], s[10:11], 0, v[134:135]
	s_add_i32 m0, s40, 0x2000
	s_nop 0
	global_load_lds_dwordx4 v[140:141], off
	v_lshl_add_u64 v[140:141], v[212:213], 0, s[34:35]
	s_mov_b32 m0, s43
	s_nop 0
	global_load_lds_dwordx4 v[140:141], off
	v_lshl_add_u64 v[140:141], v[214:215], 0, s[34:35]
	s_mov_b32 m0, s44
	s_nop 0
	global_load_lds_dwordx4 v[140:141], off
	s_waitcnt vmcnt(8)
	s_waitcnt lgkmcnt(0)
	s_setprio 1
	s_barrier
	v_mfma_f32_16x16x32_bf16 v[62:65], v[146:149], v[178:181], v[62:65]
	v_mfma_f32_16x16x32_bf16 v[58:61], v[154:157], v[178:181], v[58:61]
	v_mfma_f32_16x16x32_bf16 v[54:57], v[146:149], v[186:189], v[54:57]
	v_mfma_f32_16x16x32_bf16 v[46:49], v[154:157], v[186:189], v[46:49]
	v_mfma_f32_16x16x32_bf16 v[38:41], v[146:149], v[194:197], v[38:41]
	v_mfma_f32_16x16x32_bf16 v[30:33], v[154:157], v[194:197], v[30:33]
	v_mfma_f32_16x16x32_bf16 v[22:25], v[146:149], v[202:205], v[22:25]
	v_mfma_f32_16x16x32_bf16 v[14:17], v[154:157], v[202:205], v[14:17]
	v_mfma_f32_16x16x32_bf16 v[62:65], v[150:153], v[182:185], v[62:65]
	v_mfma_f32_16x16x32_bf16 v[58:61], v[158:161], v[182:185], v[58:61]
	v_mfma_f32_16x16x32_bf16 v[54:57], v[150:153], v[190:193], v[54:57]
	v_mfma_f32_16x16x32_bf16 v[46:49], v[158:161], v[190:193], v[46:49]
	v_mfma_f32_16x16x32_bf16 v[38:41], v[150:153], v[198:201], v[38:41]
	v_mfma_f32_16x16x32_bf16 v[30:33], v[158:161], v[198:201], v[30:33]
	v_mfma_f32_16x16x32_bf16 v[22:25], v[150:153], v[206:209], v[22:25]
	v_mfma_f32_16x16x32_bf16 v[14:17], v[158:161], v[206:209], v[14:17]
	v_mfma_f32_16x16x32_bf16 v[50:53], v[162:165], v[178:181], v[50:53]
	v_mfma_f32_16x16x32_bf16 v[42:45], v[170:173], v[178:181], v[42:45]
	v_mfma_f32_16x16x32_bf16 v[34:37], v[162:165], v[186:189], v[34:37]
	v_mfma_f32_16x16x32_bf16 v[26:29], v[170:173], v[186:189], v[26:29]
	v_mfma_f32_16x16x32_bf16 v[18:21], v[162:165], v[194:197], v[18:21]
	v_mfma_f32_16x16x32_bf16 v[10:13], v[170:173], v[194:197], v[10:13]
	v_mfma_f32_16x16x32_bf16 v[6:9], v[162:165], v[202:205], v[6:9]
	v_mfma_f32_16x16x32_bf16 v[2:5], v[170:173], v[202:205], v[2:5]
	v_mfma_f32_16x16x32_bf16 v[50:53], v[166:169], v[182:185], v[50:53]
	v_mfma_f32_16x16x32_bf16 v[42:45], v[174:177], v[182:185], v[42:45]
	v_mfma_f32_16x16x32_bf16 v[34:37], v[166:169], v[190:193], v[34:37]
	v_mfma_f32_16x16x32_bf16 v[26:29], v[174:177], v[190:193], v[26:29]
	v_mfma_f32_16x16x32_bf16 v[18:21], v[166:169], v[198:201], v[18:21]
	v_mfma_f32_16x16x32_bf16 v[10:13], v[174:177], v[198:201], v[10:13]
	v_mfma_f32_16x16x32_bf16 v[6:9], v[166:169], v[206:209], v[6:9]
	v_mfma_f32_16x16x32_bf16 v[2:5], v[174:177], v[206:209], v[2:5]
	s_barrier
	s_setprio 0
	s_add_i32 s54, s54, 2
	s_add_u32 s36, s36, 0x100
	s_addc_u32 s37, s37, 0
	s_add_u32 s52, s52, 0x100
	s_addc_u32 s53, s53, 0
	s_cmp_gt_u32 s54, 29
	s_cbranch_scc0 .LBB0_599
	s_and_b64 vcc, exec, s[12:13]
	s_cbranch_vccz .LBB0_602
	s_barrier
